# RWKV step: S.a in two chains + add, S.r_prev single chain
# speedup vs baseline: 1.0037x; 1.0037x over previous
; DEVINL u16 f2bf(float a) { return (u16)(pk2(a, 0.f) & 0xffffu); }
; template <int DIR>
; DEVINL void rwkv_scan_dir(const Params& p, int task, int lane, int wave) {
;     ...
;     if (st > 0) { const int q0 = st - 16 + seg; yo[(long)(DIR ? (4095 - q0) : q0) * 1024] = f2bf(ykeep); }
.Lrw_ready_d0:
	s_add_u32 s3, s40, s41
	s_and_b32 s3, s3, 0x1ffff
	s_add_u32 s3, s3, 16
	s_mov_b32 m0, s3
	s_nop 0
	global_load_lds_dwordx4 v5, s[10:11] offset:0
	global_load_lds_dwordx4 v5, s[10:11] offset:1024
	global_load_lds_dwordx4 v5, s[10:11] offset:2048
	global_load_lds_dwordx4 v5, s[10:11] offset:3072
	s_add_u32 s10, s10, 0x4000
	s_addc_u32 s11, s11, 0
	s_add_u32 s41, s41, 0x4000
	s_and_b32 s41, s41, 0x1ffff
	ds_read_b64 v[72:73], v6 offset:2064
	ds_read_b128 v[74:77], v6 offset:2320
	ds_read_b128 v[78:81], v6 offset:2576
	ds_read_u16 v82, v7 offset:2064
	v_fma_mix_f32 v14, v10, v26, 0 op_sel:[0,0,0] op_sel_hi:[0,1,0]
	v_fma_mix_f32 v15, v12, v27, 0 op_sel:[0,0,0] op_sel_hi:[0,1,0]
	v_fma_mix_f32 v14, v11, v26, v14 op_sel:[0,1,0] op_sel_hi:[0,1,0]
	v_fma_mix_f32 v15, v13, v27, v15 op_sel:[0,1,0] op_sel_hi:[0,1,0]
	v_fma_mix_f32 v63, v10, v92, 0 op_sel:[0,0,0] op_sel_hi:[0,1,0]
	v_fma_mix_f32 v16, v10, v24, 0 op_sel:[0,0,0] op_sel_hi:[0,1,0]
	v_add_f32_e32 v20, v14, v15
	v_fma_mix_f32 v63, v11, v92, v63 op_sel:[0,1,0] op_sel_hi:[0,1,0]
	v_fma_mix_f32 v17, v11, v24, 0 op_sel:[0,1,0] op_sel_hi:[0,1,0]
	v_add_f32_dpp v20, v20, v20 quad_perm:[1,0,3,2] row_mask:0xf bank_mask:0xf bound_ctrl:1
	v_fma_mix_f32 v63, v12, v93, v63 op_sel:[0,0,0] op_sel_hi:[0,1,0]
	v_fma_mix_f32 v18, v12, v25, 0 op_sel:[0,0,0] op_sel_hi:[0,1,0]
	v_add_f32_dpp v20, v20, v20 quad_perm:[2,3,0,1] row_mask:0xf bank_mask:0xf bound_ctrl:1
	v_fma_mix_f32 v63, v13, v93, v63 op_sel:[0,1,0] op_sel_hi:[0,1,0]
	v_fma_mix_f32 v19, v13, v25, 0 op_sel:[0,1,0] op_sel_hi:[0,1,0]
	v_add_f32_dpp v20, v20, v20 row_half_mirror row_mask:0xf bank_mask:0xf bound_ctrl:1
	v_fma_mix_f32 v16, v34, v30, v16 op_sel:[0,0,0] op_sel_hi:[1,1,0]
	v_fma_mix_f32 v17, v34, v30, v17 op_sel:[0,1,0] op_sel_hi:[1,1,0]
	v_add_f32_dpp v20, v20, v20 row_mirror row_mask:0xf bank_mask:0xf bound_ctrl:1
	v_fma_mix_f32 v18, v34, v31, v18 op_sel:[0,0,0] op_sel_hi:[1,1,0]
	v_fma_mix_f32 v19, v34, v31, v19 op_sel:[0,1,0] op_sel_hi:[1,1,0]
	v_fma_mix_f32 v10, v20, v28, v16 op_sel:[0,0,0] op_sel_hi:[0,1,0]
	v_fma_mix_f32 v11, v20, v28, v17 op_sel:[0,1,0] op_sel_hi:[0,1,0]
	v_fma_mix_f32 v12, v20, v29, v18 op_sel:[0,0,0] op_sel_hi:[0,1,0]
	v_fma_mix_f32 v13, v20, v29, v19 op_sel:[0,1,0] op_sel_hi:[0,1,0]
	s_waitcnt lgkmcnt(4)
	s_cmp_eq_u32 s14, 0
	s_cbranch_scc1 .Lrw_skip_d0
	v_add_f32_dpp v48, v48, v48 row_ror:8 row_mask:0xf bank_mask:0x3
	v_add_f32_dpp v49, v49, v49 row_ror:8 row_mask:0xf bank_mask:0x3
	v_add_f32_dpp v50, v50, v50 row_ror:8 row_mask:0xf bank_mask:0x3
	v_add_f32_dpp v51, v51, v51 row_ror:8 row_mask:0xf bank_mask:0x3
	v_add_f32_dpp v52, v52, v52 row_ror:8 row_mask:0xf bank_mask:0x3
	v_add_f32_dpp v53, v53, v53 row_ror:8 row_mask:0xf bank_mask:0x3
	v_add_f32_dpp v54, v54, v54 row_ror:8 row_mask:0xf bank_mask:0x3
	v_add_f32_dpp v55, v55, v55 row_ror:8 row_mask:0xf bank_mask:0x3
	v_add_f32_dpp v48, v56, v56 row_ror:8 row_mask:0xf bank_mask:0xc
	v_add_f32_dpp v49, v57, v57 row_ror:8 row_mask:0xf bank_mask:0xc
	v_add_f32_dpp v50, v58, v58 row_ror:8 row_mask:0xf bank_mask:0xc
	v_add_f32_dpp v51, v59, v59 row_ror:8 row_mask:0xf bank_mask:0xc
	v_add_f32_dpp v52, v60, v60 row_ror:8 row_mask:0xf bank_mask:0xc
	v_add_f32_dpp v53, v61, v61 row_ror:8 row_mask:0xf bank_mask:0xc
	v_add_f32_dpp v54, v62, v62 row_ror:8 row_mask:0xf bank_mask:0xc
	v_add_f32_dpp v55, v63, v63 row_ror:8 row_mask:0xf bank_mask:0xc
	v_add_f32_dpp v48, v48, v48 row_ror:12 row_mask:0xf bank_mask:0x5
	v_add_f32_dpp v49, v49, v49 row_ror:12 row_mask:0xf bank_mask:0x5
	v_add_f32_dpp v50, v50, v50 row_ror:12 row_mask:0xf bank_mask:0x5
	v_add_f32_dpp v51, v51, v51 row_ror:12 row_mask:0xf bank_mask:0x5
	v_add_f32_dpp v48, v52, v52 row_ror:4 row_mask:0xf bank_mask:0xa
	v_add_f32_dpp v49, v53, v53 row_ror:4 row_mask:0xf bank_mask:0xa
	v_add_f32_dpp v50, v54, v54 row_ror:4 row_mask:0xf bank_mask:0xa
	v_add_f32_dpp v51, v55, v55 row_ror:4 row_mask:0xf bank_mask:0xa
	v_add_f32_dpp v64, v48, v48 quad_perm:[2,3,0,1] row_mask:0xf bank_mask:0xf bound_ctrl:1
	v_add_f32_dpp v65, v50, v50 quad_perm:[2,3,0,1] row_mask:0xf bank_mask:0xf bound_ctrl:1
	v_cndmask_b32_e64 v56, v64, v65, s[50:51]
	v_add_f32_dpp v64, v49, v49 quad_perm:[2,3,0,1] row_mask:0xf bank_mask:0xf bound_ctrl:1
	v_add_f32_dpp v65, v51, v51 quad_perm:[2,3,0,1] row_mask:0xf bank_mask:0xf bound_ctrl:1
	v_cndmask_b32_e64 v57, v64, v65, s[50:51]
	v_add_f32_dpp v64, v56, v56 quad_perm:[1,0,3,2] row_mask:0xf bank_mask:0xf bound_ctrl:1
	s_nop 0
	v_add_f32_dpp v65, v57, v57 quad_perm:[1,0,3,2] row_mask:0xf bank_mask:0xf bound_ctrl:1
	v_cndmask_b32_e64 v66, v64, v65, s[48:49]
	v_cvt_pk_bf16_f32 v66, v66, v66
	global_store_short v8, v66, s[12:13]
	s_add_u32 s12, s12, 0x8000
	s_addc_u32 s13, s13, 0
.Lrw_skip_d0:
	ds_read_b64 v[84:85], v6 offset:3088
	ds_read_b128 v[86:89], v6 offset:3344
	ds_read_b128 v[90:93], v6 offset:3600
	ds_read_u16 v94, v7 offset:3088
	v_fma_mix_f32 v14, v10, v38, 0 op_sel:[0,0,0] op_sel_hi:[0,1,0]
	v_fma_mix_f32 v15, v12, v39, 0 op_sel:[0,0,0] op_sel_hi:[0,1,0]
	v_fma_mix_f32 v14, v11, v38, v14 op_sel:[0,1,0] op_sel_hi:[0,1,0]
	v_fma_mix_f32 v15, v13, v39, v15 op_sel:[0,1,0] op_sel_hi:[0,1,0]
	v_fma_mix_f32 v48, v10, v32, 0 op_sel:[0,0,0] op_sel_hi:[0,1,0]
	v_fma_mix_f32 v16, v10, v36, 0 op_sel:[0,0,0] op_sel_hi:[0,1,0]
	v_add_f32_e32 v20, v14, v15
	v_fma_mix_f32 v48, v11, v32, v48 op_sel:[0,1,0] op_sel_hi:[0,1,0]
	v_fma_mix_f32 v17, v11, v36, 0 op_sel:[0,1,0] op_sel_hi:[0,1,0]
	v_add_f32_dpp v20, v20, v20 quad_perm:[1,0,3,2] row_mask:0xf bank_mask:0xf bound_ctrl:1
	v_fma_mix_f32 v48, v12, v33, v48 op_sel:[0,0,0] op_sel_hi:[0,1,0]
	v_fma_mix_f32 v18, v12, v37, 0 op_sel:[0,0,0] op_sel_hi:[0,1,0]
	v_add_f32_dpp v20, v20, v20 quad_perm:[2,3,0,1] row_mask:0xf bank_mask:0xf bound_ctrl:1
	v_fma_mix_f32 v48, v13, v33, v48 op_sel:[0,1,0] op_sel_hi:[0,1,0]
	v_fma_mix_f32 v19, v13, v37, 0 op_sel:[0,1,0] op_sel_hi:[0,1,0]
	v_add_f32_dpp v20, v20, v20 row_half_mirror row_mask:0xf bank_mask:0xf bound_ctrl:1
	v_fma_mix_f32 v16, v46, v42, v16 op_sel:[0,0,0] op_sel_hi:[1,1,0]
	v_fma_mix_f32 v17, v46, v42, v17 op_sel:[0,1,0] op_sel_hi:[1,1,0]
	v_add_f32_dpp v20, v20, v20 row_mirror row_mask:0xf bank_mask:0xf bound_ctrl:1
	v_fma_mix_f32 v18, v46, v43, v18 op_sel:[0,0,0] op_sel_hi:[1,1,0]
	v_fma_mix_f32 v19, v46, v43, v19 op_sel:[0,1,0] op_sel_hi:[1,1,0]
	v_fma_mix_f32 v10, v20, v40, v16 op_sel:[0,0,0] op_sel_hi:[0,1,0]
	v_fma_mix_f32 v11, v20, v40, v17 op_sel:[0,1,0] op_sel_hi:[0,1,0]
	v_fma_mix_f32 v12, v20, v41, v18 op_sel:[0,0,0] op_sel_hi:[0,1,0]
	v_fma_mix_f32 v13, v20, v41, v19 op_sel:[0,1,0] op_sel_hi:[0,1,0]
	s_waitcnt lgkmcnt(4)
	ds_read_b64 v[24:25], v6 offset:4112
	ds_read_b128 v[26:29], v6 offset:4368
	ds_read_b128 v[30:33], v6 offset:4624
	ds_read_u16 v34, v7 offset:4112
	v_fma_mix_f32 v14, v10, v74, 0 op_sel:[0,0,0] op_sel_hi:[0,1,0]
	v_fma_mix_f32 v15, v12, v75, 0 op_sel:[0,0,0] op_sel_hi:[0,1,0]
	v_fma_mix_f32 v14, v11, v74, v14 op_sel:[0,1,0] op_sel_hi:[0,1,0]
	v_fma_mix_f32 v15, v13, v75, v15 op_sel:[0,1,0] op_sel_hi:[0,1,0]
	v_fma_mix_f32 v49, v10, v44, 0 op_sel:[0,0,0] op_sel_hi:[0,1,0]
	v_fma_mix_f32 v16, v10, v72, 0 op_sel:[0,0,0] op_sel_hi:[0,1,0]
	v_add_f32_e32 v20, v14, v15
	v_fma_mix_f32 v49, v11, v44, v49 op_sel:[0,1,0] op_sel_hi:[0,1,0]
	v_fma_mix_f32 v17, v11, v72, 0 op_sel:[0,1,0] op_sel_hi:[0,1,0]
	v_add_f32_dpp v20, v20, v20 quad_perm:[1,0,3,2] row_mask:0xf bank_mask:0xf bound_ctrl:1
	v_fma_mix_f32 v49, v12, v45, v49 op_sel:[0,0,0] op_sel_hi:[0,1,0]
	v_fma_mix_f32 v18, v12, v73, 0 op_sel:[0,0,0] op_sel_hi:[0,1,0]
	v_add_f32_dpp v20, v20, v20 quad_perm:[2,3,0,1] row_mask:0xf bank_mask:0xf bound_ctrl:1
	v_fma_mix_f32 v49, v13, v45, v49 op_sel:[0,1,0] op_sel_hi:[0,1,0]
	v_fma_mix_f32 v19, v13, v73, 0 op_sel:[0,1,0] op_sel_hi:[0,1,0]
	v_add_f32_dpp v20, v20, v20 row_half_mirror row_mask:0xf bank_mask:0xf bound_ctrl:1
	v_fma_mix_f32 v16, v82, v78, v16 op_sel:[0,0,0] op_sel_hi:[1,1,0]
	v_fma_mix_f32 v17, v82, v78, v17 op_sel:[0,1,0] op_sel_hi:[1,1,0]
	v_add_f32_dpp v20, v20, v20 row_mirror row_mask:0xf bank_mask:0xf bound_ctrl:1
	v_fma_mix_f32 v18, v82, v79, v18 op_sel:[0,0,0] op_sel_hi:[1,1,0]
	v_fma_mix_f32 v19, v82, v79, v19 op_sel:[0,1,0] op_sel_hi:[1,1,0]
	v_fma_mix_f32 v10, v20, v76, v16 op_sel:[0,0,0] op_sel_hi:[0,1,0]
	v_fma_mix_f32 v11, v20, v76, v17 op_sel:[0,1,0] op_sel_hi:[0,1,0]
	v_fma_mix_f32 v12, v20, v77, v18 op_sel:[0,0,0] op_sel_hi:[0,1,0]
	v_fma_mix_f32 v13, v20, v77, v19 op_sel:[0,1,0] op_sel_hi:[0,1,0]
	s_waitcnt lgkmcnt(4)
	ds_read_b64 v[36:37], v6 offset:5136
	ds_read_b128 v[38:41], v6 offset:5392
	ds_read_b128 v[42:45], v6 offset:5648
	ds_read_u16 v46, v7 offset:5136
	v_fma_mix_f32 v14, v10, v86, 0 op_sel:[0,0,0] op_sel_hi:[0,1,0]
	v_fma_mix_f32 v15, v12, v87, 0 op_sel:[0,0,0] op_sel_hi:[0,1,0]
	v_fma_mix_f32 v14, v11, v86, v14 op_sel:[0,1,0] op_sel_hi:[0,1,0]
	v_fma_mix_f32 v15, v13, v87, v15 op_sel:[0,1,0] op_sel_hi:[0,1,0]
	v_fma_mix_f32 v50, v10, v80, 0 op_sel:[0,0,0] op_sel_hi:[0,1,0]
	v_fma_mix_f32 v16, v10, v84, 0 op_sel:[0,0,0] op_sel_hi:[0,1,0]
	v_add_f32_e32 v20, v14, v15
	v_fma_mix_f32 v50, v11, v80, v50 op_sel:[0,1,0] op_sel_hi:[0,1,0]
	v_fma_mix_f32 v17, v11, v84, 0 op_sel:[0,1,0] op_sel_hi:[0,1,0]
	v_add_f32_dpp v20, v20, v20 quad_perm:[1,0,3,2] row_mask:0xf bank_mask:0xf bound_ctrl:1
	v_fma_mix_f32 v50, v12, v81, v50 op_sel:[0,0,0] op_sel_hi:[0,1,0]
	v_fma_mix_f32 v18, v12, v85, 0 op_sel:[0,0,0] op_sel_hi:[0,1,0]
	v_add_f32_dpp v20, v20, v20 quad_perm:[2,3,0,1] row_mask:0xf bank_mask:0xf bound_ctrl:1
	v_fma_mix_f32 v50, v13, v81, v50 op_sel:[0,1,0] op_sel_hi:[0,1,0]
	v_fma_mix_f32 v19, v13, v85, 0 op_sel:[0,1,0] op_sel_hi:[0,1,0]
	v_add_f32_dpp v20, v20, v20 row_half_mirror row_mask:0xf bank_mask:0xf bound_ctrl:1
	v_fma_mix_f32 v16, v94, v90, v16 op_sel:[0,0,0] op_sel_hi:[1,1,0]
	v_fma_mix_f32 v17, v94, v90, v17 op_sel:[0,1,0] op_sel_hi:[1,1,0]
	v_add_f32_dpp v20, v20, v20 row_mirror row_mask:0xf bank_mask:0xf bound_ctrl:1
	v_fma_mix_f32 v18, v94, v91, v18 op_sel:[0,0,0] op_sel_hi:[1,1,0]
	v_fma_mix_f32 v19, v94, v91, v19 op_sel:[0,1,0] op_sel_hi:[1,1,0]
	v_fma_mix_f32 v10, v20, v88, v16 op_sel:[0,0,0] op_sel_hi:[0,1,0]
	v_fma_mix_f32 v11, v20, v88, v17 op_sel:[0,1,0] op_sel_hi:[0,1,0]
	v_fma_mix_f32 v12, v20, v89, v18 op_sel:[0,0,0] op_sel_hi:[0,1,0]
	v_fma_mix_f32 v13, v20, v89, v19 op_sel:[0,1,0] op_sel_hi:[0,1,0]
	s_waitcnt lgkmcnt(4)
	ds_read_b64 v[72:73], v6 offset:6160
	ds_read_b128 v[74:77], v6 offset:6416
	ds_read_b128 v[78:81], v6 offset:6672
	ds_read_u16 v82, v7 offset:6160
	v_fma_mix_f32 v14, v10, v26, 0 op_sel:[0,0,0] op_sel_hi:[0,1,0]
	v_fma_mix_f32 v15, v12, v27, 0 op_sel:[0,0,0] op_sel_hi:[0,1,0]
	v_fma_mix_f32 v14, v11, v26, v14 op_sel:[0,1,0] op_sel_hi:[0,1,0]
	v_fma_mix_f32 v15, v13, v27, v15 op_sel:[0,1,0] op_sel_hi:[0,1,0]
	v_fma_mix_f32 v51, v10, v92, 0 op_sel:[0,0,0] op_sel_hi:[0,1,0]
	v_fma_mix_f32 v16, v10, v24, 0 op_sel:[0,0,0] op_sel_hi:[0,1,0]
	v_add_f32_e32 v20, v14, v15
	v_fma_mix_f32 v51, v11, v92, v51 op_sel:[0,1,0] op_sel_hi:[0,1,0]
	v_fma_mix_f32 v17, v11, v24, 0 op_sel:[0,1,0] op_sel_hi:[0,1,0]
	v_add_f32_dpp v20, v20, v20 quad_perm:[1,0,3,2] row_mask:0xf bank_mask:0xf bound_ctrl:1
	v_fma_mix_f32 v51, v12, v93, v51 op_sel:[0,0,0] op_sel_hi:[0,1,0]
	v_fma_mix_f32 v18, v12, v25, 0 op_sel:[0,0,0] op_sel_hi:[0,1,0]
	v_add_f32_dpp v20, v20, v20 quad_perm:[2,3,0,1] row_mask:0xf bank_mask:0xf bound_ctrl:1
	v_fma_mix_f32 v51, v13, v93, v51 op_sel:[0,1,0] op_sel_hi:[0,1,0]
	v_fma_mix_f32 v19, v13, v25, 0 op_sel:[0,1,0] op_sel_hi:[0,1,0]
	v_add_f32_dpp v20, v20, v20 row_half_mirror row_mask:0xf bank_mask:0xf bound_ctrl:1
	v_fma_mix_f32 v16, v34, v30, v16 op_sel:[0,0,0] op_sel_hi:[1,1,0]
	v_fma_mix_f32 v17, v34, v30, v17 op_sel:[0,1,0] op_sel_hi:[1,1,0]
	v_add_f32_dpp v20, v20, v20 row_mirror row_mask:0xf bank_mask:0xf bound_ctrl:1
	v_fma_mix_f32 v18, v34, v31, v18 op_sel:[0,0,0] op_sel_hi:[1,1,0]
	v_fma_mix_f32 v19, v34, v31, v19 op_sel:[0,1,0] op_sel_hi:[1,1,0]
	v_fma_mix_f32 v10, v20, v28, v16 op_sel:[0,0,0] op_sel_hi:[0,1,0]
	v_fma_mix_f32 v11, v20, v28, v17 op_sel:[0,1,0] op_sel_hi:[0,1,0]
	v_fma_mix_f32 v12, v20, v29, v18 op_sel:[0,0,0] op_sel_hi:[0,1,0]
	v_fma_mix_f32 v13, v20, v29, v19 op_sel:[0,1,0] op_sel_hi:[0,1,0]
	s_waitcnt lgkmcnt(4)
	ds_read_b64 v[84:85], v6 offset:7184
	ds_read_b128 v[86:89], v6 offset:7440
	ds_read_b128 v[90:93], v6 offset:7696
	ds_read_u16 v94, v7 offset:7184
	v_fma_mix_f32 v14, v10, v38, 0 op_sel:[0,0,0] op_sel_hi:[0,1,0]
	v_fma_mix_f32 v15, v12, v39, 0 op_sel:[0,0,0] op_sel_hi:[0,1,0]
	v_fma_mix_f32 v14, v11, v38, v14 op_sel:[0,1,0] op_sel_hi:[0,1,0]
	v_fma_mix_f32 v15, v13, v39, v15 op_sel:[0,1,0] op_sel_hi:[0,1,0]
	v_fma_mix_f32 v52, v10, v32, 0 op_sel:[0,0,0] op_sel_hi:[0,1,0]
	v_fma_mix_f32 v16, v10, v36, 0 op_sel:[0,0,0] op_sel_hi:[0,1,0]
	v_add_f32_e32 v20, v14, v15
	v_fma_mix_f32 v52, v11, v32, v52 op_sel:[0,1,0] op_sel_hi:[0,1,0]
	v_fma_mix_f32 v17, v11, v36, 0 op_sel:[0,1,0] op_sel_hi:[0,1,0]
	v_add_f32_dpp v20, v20, v20 quad_perm:[1,0,3,2] row_mask:0xf bank_mask:0xf bound_ctrl:1
	v_fma_mix_f32 v52, v12, v33, v52 op_sel:[0,0,0] op_sel_hi:[0,1,0]
	v_fma_mix_f32 v18, v12, v37, 0 op_sel:[0,0,0] op_sel_hi:[0,1,0]
	v_add_f32_dpp v20, v20, v20 quad_perm:[2,3,0,1] row_mask:0xf bank_mask:0xf bound_ctrl:1
	v_fma_mix_f32 v52, v13, v33, v52 op_sel:[0,1,0] op_sel_hi:[0,1,0]
	v_fma_mix_f32 v19, v13, v37, 0 op_sel:[0,1,0] op_sel_hi:[0,1,0]
	v_add_f32_dpp v20, v20, v20 row_half_mirror row_mask:0xf bank_mask:0xf bound_ctrl:1
	v_fma_mix_f32 v16, v46, v42, v16 op_sel:[0,0,0] op_sel_hi:[1,1,0]
	v_fma_mix_f32 v17, v46, v42, v17 op_sel:[0,1,0] op_sel_hi:[1,1,0]
	v_add_f32_dpp v20, v20, v20 row_mirror row_mask:0xf bank_mask:0xf bound_ctrl:1
	v_fma_mix_f32 v18, v46, v43, v18 op_sel:[0,0,0] op_sel_hi:[1,1,0]
	v_fma_mix_f32 v19, v46, v43, v19 op_sel:[0,1,0] op_sel_hi:[1,1,0]
	v_fma_mix_f32 v10, v20, v40, v16 op_sel:[0,0,0] op_sel_hi:[0,1,0]
	v_fma_mix_f32 v11, v20, v40, v17 op_sel:[0,1,0] op_sel_hi:[0,1,0]
	v_fma_mix_f32 v12, v20, v41, v18 op_sel:[0,0,0] op_sel_hi:[0,1,0]
	v_fma_mix_f32 v13, v20, v41, v19 op_sel:[0,1,0] op_sel_hi:[0,1,0]
	s_waitcnt lgkmcnt(4)
	ds_read_b64 v[24:25], v6 offset:8208
	ds_read_b128 v[26:29], v6 offset:8464
	ds_read_b128 v[30:33], v6 offset:8720
	ds_read_u16 v34, v7 offset:8208
	v_fma_mix_f32 v14, v10, v74, 0 op_sel:[0,0,0] op_sel_hi:[0,1,0]
	v_fma_mix_f32 v15, v12, v75, 0 op_sel:[0,0,0] op_sel_hi:[0,1,0]
	v_fma_mix_f32 v14, v11, v74, v14 op_sel:[0,1,0] op_sel_hi:[0,1,0]
	v_fma_mix_f32 v15, v13, v75, v15 op_sel:[0,1,0] op_sel_hi:[0,1,0]
	v_fma_mix_f32 v53, v10, v44, 0 op_sel:[0,0,0] op_sel_hi:[0,1,0]
	v_fma_mix_f32 v16, v10, v72, 0 op_sel:[0,0,0] op_sel_hi:[0,1,0]
	v_add_f32_e32 v20, v14, v15
	v_fma_mix_f32 v53, v11, v44, v53 op_sel:[0,1,0] op_sel_hi:[0,1,0]
	v_fma_mix_f32 v17, v11, v72, 0 op_sel:[0,1,0] op_sel_hi:[0,1,0]
	v_add_f32_dpp v20, v20, v20 quad_perm:[1,0,3,2] row_mask:0xf bank_mask:0xf bound_ctrl:1
	v_fma_mix_f32 v53, v12, v45, v53 op_sel:[0,0,0] op_sel_hi:[0,1,0]
	v_fma_mix_f32 v18, v12, v73, 0 op_sel:[0,0,0] op_sel_hi:[0,1,0]
	v_add_f32_dpp v20, v20, v20 quad_perm:[2,3,0,1] row_mask:0xf bank_mask:0xf bound_ctrl:1
	v_fma_mix_f32 v53, v13, v45, v53 op_sel:[0,1,0] op_sel_hi:[0,1,0]
	v_fma_mix_f32 v19, v13, v73, 0 op_sel:[0,1,0] op_sel_hi:[0,1,0]
	v_add_f32_dpp v20, v20, v20 row_half_mirror row_mask:0xf bank_mask:0xf bound_ctrl:1
	v_fma_mix_f32 v16, v82, v78, v16 op_sel:[0,0,0] op_sel_hi:[1,1,0]
	v_fma_mix_f32 v17, v82, v78, v17 op_sel:[0,1,0] op_sel_hi:[1,1,0]
	v_add_f32_dpp v20, v20, v20 row_mirror row_mask:0xf bank_mask:0xf bound_ctrl:1
	v_fma_mix_f32 v18, v82, v79, v18 op_sel:[0,0,0] op_sel_hi:[1,1,0]
	v_fma_mix_f32 v19, v82, v79, v19 op_sel:[0,1,0] op_sel_hi:[1,1,0]
	v_fma_mix_f32 v10, v20, v76, v16 op_sel:[0,0,0] op_sel_hi:[0,1,0]
	v_fma_mix_f32 v11, v20, v76, v17 op_sel:[0,1,0] op_sel_hi:[0,1,0]
	v_fma_mix_f32 v12, v20, v77, v18 op_sel:[0,0,0] op_sel_hi:[0,1,0]
	v_fma_mix_f32 v13, v20, v77, v19 op_sel:[0,1,0] op_sel_hi:[0,1,0]
	s_waitcnt lgkmcnt(4)
	ds_read_b64 v[36:37], v6 offset:9232
	ds_read_b128 v[38:41], v6 offset:9488
	ds_read_b128 v[42:45], v6 offset:9744
	ds_read_u16 v46, v7 offset:9232
	v_fma_mix_f32 v14, v10, v86, 0 op_sel:[0,0,0] op_sel_hi:[0,1,0]
	v_fma_mix_f32 v15, v12, v87, 0 op_sel:[0,0,0] op_sel_hi:[0,1,0]
	v_fma_mix_f32 v14, v11, v86, v14 op_sel:[0,1,0] op_sel_hi:[0,1,0]
	v_fma_mix_f32 v15, v13, v87, v15 op_sel:[0,1,0] op_sel_hi:[0,1,0]
	v_fma_mix_f32 v54, v10, v80, 0 op_sel:[0,0,0] op_sel_hi:[0,1,0]
	v_fma_mix_f32 v16, v10, v84, 0 op_sel:[0,0,0] op_sel_hi:[0,1,0]
	v_add_f32_e32 v20, v14, v15
	v_fma_mix_f32 v54, v11, v80, v54 op_sel:[0,1,0] op_sel_hi:[0,1,0]
	v_fma_mix_f32 v17, v11, v84, 0 op_sel:[0,1,0] op_sel_hi:[0,1,0]
	v_add_f32_dpp v20, v20, v20 quad_perm:[1,0,3,2] row_mask:0xf bank_mask:0xf bound_ctrl:1
	v_fma_mix_f32 v54, v12, v81, v54 op_sel:[0,0,0] op_sel_hi:[0,1,0]
	v_fma_mix_f32 v18, v12, v85, 0 op_sel:[0,0,0] op_sel_hi:[0,1,0]
	v_add_f32_dpp v20, v20, v20 quad_perm:[2,3,0,1] row_mask:0xf bank_mask:0xf bound_ctrl:1
	v_fma_mix_f32 v54, v13, v81, v54 op_sel:[0,1,0] op_sel_hi:[0,1,0]
	v_fma_mix_f32 v19, v13, v85, 0 op_sel:[0,1,0] op_sel_hi:[0,1,0]
	v_add_f32_dpp v20, v20, v20 row_half_mirror row_mask:0xf bank_mask:0xf bound_ctrl:1
	v_fma_mix_f32 v16, v94, v90, v16 op_sel:[0,0,0] op_sel_hi:[1,1,0]
	v_fma_mix_f32 v17, v94, v90, v17 op_sel:[0,1,0] op_sel_hi:[1,1,0]
	v_add_f32_dpp v20, v20, v20 row_mirror row_mask:0xf bank_mask:0xf bound_ctrl:1
	v_fma_mix_f32 v18, v94, v91, v18 op_sel:[0,0,0] op_sel_hi:[1,1,0]
	v_fma_mix_f32 v19, v94, v91, v19 op_sel:[0,1,0] op_sel_hi:[1,1,0]
	v_fma_mix_f32 v10, v20, v88, v16 op_sel:[0,0,0] op_sel_hi:[0,1,0]
	v_fma_mix_f32 v11, v20, v88, v17 op_sel:[0,1,0] op_sel_hi:[0,1,0]
	v_fma_mix_f32 v12, v20, v89, v18 op_sel:[0,0,0] op_sel_hi:[0,1,0]
	v_fma_mix_f32 v13, v20, v89, v19 op_sel:[0,1,0] op_sel_hi:[0,1,0]
	s_waitcnt lgkmcnt(4)
	ds_read_b64 v[72:73], v6 offset:10256
	ds_read_b128 v[74:77], v6 offset:10512
	ds_read_b128 v[78:81], v6 offset:10768
	ds_read_u16 v82, v7 offset:10256
	v_fma_mix_f32 v14, v10, v26, 0 op_sel:[0,0,0] op_sel_hi:[0,1,0]
	v_fma_mix_f32 v15, v12, v27, 0 op_sel:[0,0,0] op_sel_hi:[0,1,0]
	v_fma_mix_f32 v14, v11, v26, v14 op_sel:[0,1,0] op_sel_hi:[0,1,0]
	v_fma_mix_f32 v15, v13, v27, v15 op_sel:[0,1,0] op_sel_hi:[0,1,0]
	v_fma_mix_f32 v55, v10, v92, 0 op_sel:[0,0,0] op_sel_hi:[0,1,0]
	v_fma_mix_f32 v16, v10, v24, 0 op_sel:[0,0,0] op_sel_hi:[0,1,0]
	v_add_f32_e32 v20, v14, v15
	v_fma_mix_f32 v55, v11, v92, v55 op_sel:[0,1,0] op_sel_hi:[0,1,0]
	v_fma_mix_f32 v17, v11, v24, 0 op_sel:[0,1,0] op_sel_hi:[0,1,0]
	v_add_f32_dpp v20, v20, v20 quad_perm:[1,0,3,2] row_mask:0xf bank_mask:0xf bound_ctrl:1
	v_fma_mix_f32 v55, v12, v93, v55 op_sel:[0,0,0] op_sel_hi:[0,1,0]
	v_fma_mix_f32 v18, v12, v25, 0 op_sel:[0,0,0] op_sel_hi:[0,1,0]
	v_add_f32_dpp v20, v20, v20 quad_perm:[2,3,0,1] row_mask:0xf bank_mask:0xf bound_ctrl:1
	v_fma_mix_f32 v55, v13, v93, v55 op_sel:[0,1,0] op_sel_hi:[0,1,0]
	v_fma_mix_f32 v19, v13, v25, 0 op_sel:[0,1,0] op_sel_hi:[0,1,0]
	v_add_f32_dpp v20, v20, v20 row_half_mirror row_mask:0xf bank_mask:0xf bound_ctrl:1
	v_fma_mix_f32 v16, v34, v30, v16 op_sel:[0,0,0] op_sel_hi:[1,1,0]
	v_fma_mix_f32 v17, v34, v30, v17 op_sel:[0,1,0] op_sel_hi:[1,1,0]
	v_add_f32_dpp v20, v20, v20 row_mirror row_mask:0xf bank_mask:0xf bound_ctrl:1
	v_fma_mix_f32 v18, v34, v31, v18 op_sel:[0,0,0] op_sel_hi:[1,1,0]
	v_fma_mix_f32 v19, v34, v31, v19 op_sel:[0,1,0] op_sel_hi:[1,1,0]
	v_fma_mix_f32 v10, v20, v28, v16 op_sel:[0,0,0] op_sel_hi:[0,1,0]
	v_fma_mix_f32 v11, v20, v28, v17 op_sel:[0,1,0] op_sel_hi:[0,1,0]
	v_fma_mix_f32 v12, v20, v29, v18 op_sel:[0,0,0] op_sel_hi:[0,1,0]
	v_fma_mix_f32 v13, v20, v29, v19 op_sel:[0,1,0] op_sel_hi:[0,1,0]
	s_waitcnt lgkmcnt(4)
	ds_read_b64 v[84:85], v6 offset:11280
	ds_read_b128 v[86:89], v6 offset:11536
	ds_read_b128 v[90:93], v6 offset:11792
	ds_read_u16 v94, v7 offset:11280
	v_fma_mix_f32 v14, v10, v38, 0 op_sel:[0,0,0] op_sel_hi:[0,1,0]
	v_fma_mix_f32 v15, v12, v39, 0 op_sel:[0,0,0] op_sel_hi:[0,1,0]
	v_fma_mix_f32 v14, v11, v38, v14 op_sel:[0,1,0] op_sel_hi:[0,1,0]
	v_fma_mix_f32 v15, v13, v39, v15 op_sel:[0,1,0] op_sel_hi:[0,1,0]
	v_fma_mix_f32 v56, v10, v32, 0 op_sel:[0,0,0] op_sel_hi:[0,1,0]
	v_fma_mix_f32 v16, v10, v36, 0 op_sel:[0,0,0] op_sel_hi:[0,1,0]
	v_add_f32_e32 v20, v14, v15
	v_fma_mix_f32 v56, v11, v32, v56 op_sel:[0,1,0] op_sel_hi:[0,1,0]
	v_fma_mix_f32 v17, v11, v36, 0 op_sel:[0,1,0] op_sel_hi:[0,1,0]
	v_add_f32_dpp v20, v20, v20 quad_perm:[1,0,3,2] row_mask:0xf bank_mask:0xf bound_ctrl:1
	v_fma_mix_f32 v56, v12, v33, v56 op_sel:[0,0,0] op_sel_hi:[0,1,0]
	v_fma_mix_f32 v18, v12, v37, 0 op_sel:[0,0,0] op_sel_hi:[0,1,0]
	v_add_f32_dpp v20, v20, v20 quad_perm:[2,3,0,1] row_mask:0xf bank_mask:0xf bound_ctrl:1
	v_fma_mix_f32 v56, v13, v33, v56 op_sel:[0,1,0] op_sel_hi:[0,1,0]
	v_fma_mix_f32 v19, v13, v37, 0 op_sel:[0,1,0] op_sel_hi:[0,1,0]
	v_add_f32_dpp v20, v20, v20 row_half_mirror row_mask:0xf bank_mask:0xf bound_ctrl:1
	v_fma_mix_f32 v16, v46, v42, v16 op_sel:[0,0,0] op_sel_hi:[1,1,0]
	v_fma_mix_f32 v17, v46, v42, v17 op_sel:[0,1,0] op_sel_hi:[1,1,0]
	v_add_f32_dpp v20, v20, v20 row_mirror row_mask:0xf bank_mask:0xf bound_ctrl:1
	v_fma_mix_f32 v18, v46, v43, v18 op_sel:[0,0,0] op_sel_hi:[1,1,0]
	v_fma_mix_f32 v19, v46, v43, v19 op_sel:[0,1,0] op_sel_hi:[1,1,0]
	v_fma_mix_f32 v10, v20, v40, v16 op_sel:[0,0,0] op_sel_hi:[0,1,0]
	v_fma_mix_f32 v11, v20, v40, v17 op_sel:[0,1,0] op_sel_hi:[0,1,0]
	v_fma_mix_f32 v12, v20, v41, v18 op_sel:[0,0,0] op_sel_hi:[0,1,0]
	v_fma_mix_f32 v13, v20, v41, v19 op_sel:[0,1,0] op_sel_hi:[0,1,0]
	s_waitcnt lgkmcnt(4)
	ds_read_b64 v[24:25], v6 offset:12304
	ds_read_b128 v[26:29], v6 offset:12560
	ds_read_b128 v[30:33], v6 offset:12816
	ds_read_u16 v34, v7 offset:12304
	v_fma_mix_f32 v14, v10, v74, 0 op_sel:[0,0,0] op_sel_hi:[0,1,0]
	v_fma_mix_f32 v15, v12, v75, 0 op_sel:[0,0,0] op_sel_hi:[0,1,0]
	v_fma_mix_f32 v14, v11, v74, v14 op_sel:[0,1,0] op_sel_hi:[0,1,0]
	v_fma_mix_f32 v15, v13, v75, v15 op_sel:[0,1,0] op_sel_hi:[0,1,0]
	v_fma_mix_f32 v57, v10, v44, 0 op_sel:[0,0,0] op_sel_hi:[0,1,0]
	v_fma_mix_f32 v16, v10, v72, 0 op_sel:[0,0,0] op_sel_hi:[0,1,0]
	v_add_f32_e32 v20, v14, v15
	v_fma_mix_f32 v57, v11, v44, v57 op_sel:[0,1,0] op_sel_hi:[0,1,0]
	v_fma_mix_f32 v17, v11, v72, 0 op_sel:[0,1,0] op_sel_hi:[0,1,0]
	v_add_f32_dpp v20, v20, v20 quad_perm:[1,0,3,2] row_mask:0xf bank_mask:0xf bound_ctrl:1
	v_fma_mix_f32 v57, v12, v45, v57 op_sel:[0,0,0] op_sel_hi:[0,1,0]
	v_fma_mix_f32 v18, v12, v73, 0 op_sel:[0,0,0] op_sel_hi:[0,1,0]
	v_add_f32_dpp v20, v20, v20 quad_perm:[2,3,0,1] row_mask:0xf bank_mask:0xf bound_ctrl:1
	v_fma_mix_f32 v57, v13, v45, v57 op_sel:[0,1,0] op_sel_hi:[0,1,0]
	v_fma_mix_f32 v19, v13, v73, 0 op_sel:[0,1,0] op_sel_hi:[0,1,0]
	v_add_f32_dpp v20, v20, v20 row_half_mirror row_mask:0xf bank_mask:0xf bound_ctrl:1
	v_fma_mix_f32 v16, v82, v78, v16 op_sel:[0,0,0] op_sel_hi:[1,1,0]
	v_fma_mix_f32 v17, v82, v78, v17 op_sel:[0,1,0] op_sel_hi:[1,1,0]
	v_add_f32_dpp v20, v20, v20 row_mirror row_mask:0xf bank_mask:0xf bound_ctrl:1
	v_fma_mix_f32 v18, v82, v79, v18 op_sel:[0,0,0] op_sel_hi:[1,1,0]
	v_fma_mix_f32 v19, v82, v79, v19 op_sel:[0,1,0] op_sel_hi:[1,1,0]
	v_fma_mix_f32 v10, v20, v76, v16 op_sel:[0,0,0] op_sel_hi:[0,1,0]
	v_fma_mix_f32 v11, v20, v76, v17 op_sel:[0,1,0] op_sel_hi:[0,1,0]
	v_fma_mix_f32 v12, v20, v77, v18 op_sel:[0,0,0] op_sel_hi:[0,1,0]
	v_fma_mix_f32 v13, v20, v77, v19 op_sel:[0,1,0] op_sel_hi:[0,1,0]
	s_waitcnt lgkmcnt(4)
	ds_read_b64 v[36:37], v6 offset:13328
	ds_read_b128 v[38:41], v6 offset:13584
	ds_read_b128 v[42:45], v6 offset:13840
	ds_read_u16 v46, v7 offset:13328
	v_fma_mix_f32 v14, v10, v86, 0 op_sel:[0,0,0] op_sel_hi:[0,1,0]
	v_fma_mix_f32 v15, v12, v87, 0 op_sel:[0,0,0] op_sel_hi:[0,1,0]
	v_fma_mix_f32 v14, v11, v86, v14 op_sel:[0,1,0] op_sel_hi:[0,1,0]
	v_fma_mix_f32 v15, v13, v87, v15 op_sel:[0,1,0] op_sel_hi:[0,1,0]
	v_fma_mix_f32 v58, v10, v80, 0 op_sel:[0,0,0] op_sel_hi:[0,1,0]
	v_fma_mix_f32 v16, v10, v84, 0 op_sel:[0,0,0] op_sel_hi:[0,1,0]
	v_add_f32_e32 v20, v14, v15
	v_fma_mix_f32 v58, v11, v80, v58 op_sel:[0,1,0] op_sel_hi:[0,1,0]
	v_fma_mix_f32 v17, v11, v84, 0 op_sel:[0,1,0] op_sel_hi:[0,1,0]
	v_add_f32_dpp v20, v20, v20 quad_perm:[1,0,3,2] row_mask:0xf bank_mask:0xf bound_ctrl:1
	v_fma_mix_f32 v58, v12, v81, v58 op_sel:[0,0,0] op_sel_hi:[0,1,0]
	v_fma_mix_f32 v18, v12, v85, 0 op_sel:[0,0,0] op_sel_hi:[0,1,0]
	v_add_f32_dpp v20, v20, v20 quad_perm:[2,3,0,1] row_mask:0xf bank_mask:0xf bound_ctrl:1
	v_fma_mix_f32 v58, v13, v81, v58 op_sel:[0,1,0] op_sel_hi:[0,1,0]
	v_fma_mix_f32 v19, v13, v85, 0 op_sel:[0,1,0] op_sel_hi:[0,1,0]
	v_add_f32_dpp v20, v20, v20 row_half_mirror row_mask:0xf bank_mask:0xf bound_ctrl:1
	v_fma_mix_f32 v16, v94, v90, v16 op_sel:[0,0,0] op_sel_hi:[1,1,0]
	v_fma_mix_f32 v17, v94, v90, v17 op_sel:[0,1,0] op_sel_hi:[1,1,0]
	v_add_f32_dpp v20, v20, v20 row_mirror row_mask:0xf bank_mask:0xf bound_ctrl:1
	v_fma_mix_f32 v18, v94, v91, v18 op_sel:[0,0,0] op_sel_hi:[1,1,0]
	v_fma_mix_f32 v19, v94, v91, v19 op_sel:[0,1,0] op_sel_hi:[1,1,0]
	v_fma_mix_f32 v10, v20, v88, v16 op_sel:[0,0,0] op_sel_hi:[0,1,0]
	v_fma_mix_f32 v11, v20, v88, v17 op_sel:[0,1,0] op_sel_hi:[0,1,0]
	v_fma_mix_f32 v12, v20, v89, v18 op_sel:[0,0,0] op_sel_hi:[0,1,0]
	v_fma_mix_f32 v13, v20, v89, v19 op_sel:[0,1,0] op_sel_hi:[0,1,0]
	s_waitcnt lgkmcnt(4)
	ds_read_b64 v[72:73], v6 offset:14352
	ds_read_b128 v[74:77], v6 offset:14608
	ds_read_b128 v[78:81], v6 offset:14864
	ds_read_u16 v82, v7 offset:14352
	v_fma_mix_f32 v14, v10, v26, 0 op_sel:[0,0,0] op_sel_hi:[0,1,0]
	v_fma_mix_f32 v15, v12, v27, 0 op_sel:[0,0,0] op_sel_hi:[0,1,0]
	v_fma_mix_f32 v14, v11, v26, v14 op_sel:[0,1,0] op_sel_hi:[0,1,0]
	v_fma_mix_f32 v15, v13, v27, v15 op_sel:[0,1,0] op_sel_hi:[0,1,0]
	v_fma_mix_f32 v59, v10, v92, 0 op_sel:[0,0,0] op_sel_hi:[0,1,0]
	v_fma_mix_f32 v16, v10, v24, 0 op_sel:[0,0,0] op_sel_hi:[0,1,0]
	v_add_f32_e32 v20, v14, v15
	v_fma_mix_f32 v59, v11, v92, v59 op_sel:[0,1,0] op_sel_hi:[0,1,0]
	v_fma_mix_f32 v17, v11, v24, 0 op_sel:[0,1,0] op_sel_hi:[0,1,0]
	v_add_f32_dpp v20, v20, v20 quad_perm:[1,0,3,2] row_mask:0xf bank_mask:0xf bound_ctrl:1
	v_fma_mix_f32 v59, v12, v93, v59 op_sel:[0,0,0] op_sel_hi:[0,1,0]
	v_fma_mix_f32 v18, v12, v25, 0 op_sel:[0,0,0] op_sel_hi:[0,1,0]
	v_add_f32_dpp v20, v20, v20 quad_perm:[2,3,0,1] row_mask:0xf bank_mask:0xf bound_ctrl:1
	v_fma_mix_f32 v59, v13, v93, v59 op_sel:[0,1,0] op_sel_hi:[0,1,0]
	v_fma_mix_f32 v19, v13, v25, 0 op_sel:[0,1,0] op_sel_hi:[0,1,0]
	v_add_f32_dpp v20, v20, v20 row_half_mirror row_mask:0xf bank_mask:0xf bound_ctrl:1
	v_fma_mix_f32 v16, v34, v30, v16 op_sel:[0,0,0] op_sel_hi:[1,1,0]
	v_fma_mix_f32 v17, v34, v30, v17 op_sel:[0,1,0] op_sel_hi:[1,1,0]
	v_add_f32_dpp v20, v20, v20 row_mirror row_mask:0xf bank_mask:0xf bound_ctrl:1
	v_fma_mix_f32 v18, v34, v31, v18 op_sel:[0,0,0] op_sel_hi:[1,1,0]
	v_fma_mix_f32 v19, v34, v31, v19 op_sel:[0,1,0] op_sel_hi:[1,1,0]
	v_fma_mix_f32 v10, v20, v28, v16 op_sel:[0,0,0] op_sel_hi:[0,1,0]
	v_fma_mix_f32 v11, v20, v28, v17 op_sel:[0,1,0] op_sel_hi:[0,1,0]
	v_fma_mix_f32 v12, v20, v29, v18 op_sel:[0,0,0] op_sel_hi:[0,1,0]
	v_fma_mix_f32 v13, v20, v29, v19 op_sel:[0,1,0] op_sel_hi:[0,1,0]
	s_waitcnt lgkmcnt(4)
; DEVINL u16 f2bf(float a) { return (u16)(pk2(a, 0.f) & 0xffffu); }
; #define RW_STEP2(B) RW_STEP(B, WvA, XA, KrA, vhA, WvB, XB, KrB, vhB); RW_STEP((B) + 1, WvB, XB, KrB, vhB, WvA, XA, KrA, vhA)
; #define RW_STEP4(B) RW_STEP2(B); RW_STEP2((B) + 2)
; template <int DIR>
; DEVINL void rwkv_scan_dir(const Params& p, int task, int lane, int wave) {
;     ...
;   for (int st = 0; st < 4096; st += 32) {
;     RW_STEP(0, WvA, XA, KrA, vhA, WvB, XB, KrB, vhB);
;     if (st > 0) { const int q0 = st - 16 + seg; yo[(long)(DIR ? (4095 - q0) : q0) * 1024] = f2bf(ykeep); }
;     RW_STEP(1, WvB, XB, KrB, vhB, WvA, XA, KrA, vhA);
;     RW_STEP2(2); RW_STEP4(4); RW_STEP4(8); RW_STEP4(12);
;     RW_STEP(16, WvA, XA, KrA, vhA, WvB, XB, KrB, vhB);
;     { const int q0 = st + seg; yo[(long)(DIR ? (4095 - q0) : q0) * 1024] = f2bf(ykeep); }
;     RW_STEP(17, WvB, XB, KrB, vhB, WvA, XA, KrA, vhA);
;     RW_STEP2(18); RW_STEP4(20); RW_STEP4(24); RW_STEP4(28);
;   }
	ds_read_b128 v[100:103], v9
	ds_read_b128 v[104:107], v9 offset:16
	ds_read_b64 v[84:85], v6 offset:15376
	ds_read_b128 v[86:89], v6 offset:15632
	ds_read_b128 v[90:93], v6 offset:15888
	ds_read_u16 v94, v7 offset:15376
	v_fma_mix_f32 v14, v10, v38, 0 op_sel:[0,0,0] op_sel_hi:[0,1,0]
	v_fma_mix_f32 v15, v12, v39, 0 op_sel:[0,0,0] op_sel_hi:[0,1,0]
	v_fma_mix_f32 v14, v11, v38, v14 op_sel:[0,1,0] op_sel_hi:[0,1,0]
	v_fma_mix_f32 v15, v13, v39, v15 op_sel:[0,1,0] op_sel_hi:[0,1,0]
	v_fma_mix_f32 v60, v10, v32, 0 op_sel:[0,0,0] op_sel_hi:[0,1,0]
	v_fma_mix_f32 v16, v10, v36, 0 op_sel:[0,0,0] op_sel_hi:[0,1,0]
	v_add_f32_e32 v20, v14, v15
	v_fma_mix_f32 v60, v11, v32, v60 op_sel:[0,1,0] op_sel_hi:[0,1,0]
	v_fma_mix_f32 v17, v11, v36, 0 op_sel:[0,1,0] op_sel_hi:[0,1,0]
	v_add_f32_dpp v20, v20, v20 quad_perm:[1,0,3,2] row_mask:0xf bank_mask:0xf bound_ctrl:1
	v_fma_mix_f32 v60, v12, v33, v60 op_sel:[0,0,0] op_sel_hi:[0,1,0]
	v_fma_mix_f32 v18, v12, v37, 0 op_sel:[0,0,0] op_sel_hi:[0,1,0]
	v_add_f32_dpp v20, v20, v20 quad_perm:[2,3,0,1] row_mask:0xf bank_mask:0xf bound_ctrl:1
	v_fma_mix_f32 v60, v13, v33, v60 op_sel:[0,1,0] op_sel_hi:[0,1,0]
	v_fma_mix_f32 v19, v13, v37, 0 op_sel:[0,1,0] op_sel_hi:[0,1,0]
	v_add_f32_dpp v20, v20, v20 row_half_mirror row_mask:0xf bank_mask:0xf bound_ctrl:1
	v_fma_mix_f32 v16, v46, v42, v16 op_sel:[0,0,0] op_sel_hi:[1,1,0]
	v_fma_mix_f32 v17, v46, v42, v17 op_sel:[0,1,0] op_sel_hi:[1,1,0]
	v_add_f32_dpp v20, v20, v20 row_mirror row_mask:0xf bank_mask:0xf bound_ctrl:1
	v_fma_mix_f32 v18, v46, v43, v18 op_sel:[0,0,0] op_sel_hi:[1,1,0]
	v_fma_mix_f32 v19, v46, v43, v19 op_sel:[0,1,0] op_sel_hi:[1,1,0]
	v_fma_mix_f32 v10, v20, v40, v16 op_sel:[0,0,0] op_sel_hi:[0,1,0]
	v_fma_mix_f32 v11, v20, v40, v17 op_sel:[0,1,0] op_sel_hi:[0,1,0]
	v_fma_mix_f32 v12, v20, v41, v18 op_sel:[0,0,0] op_sel_hi:[0,1,0]
	v_fma_mix_f32 v13, v20, v41, v19 op_sel:[0,1,0] op_sel_hi:[0,1,0]
	s_waitcnt lgkmcnt(4)
	v_add_u32_e32 v6, 0x4000, v6
	v_add_u32_e32 v7, 0x4000, v7
	v_and_b32_e32 v6, 0x1ffff, v6
	v_and_b32_e32 v7, 0x1ffff, v7
	ds_read_b64 v[24:25], v6 offset:16
	ds_read_b128 v[26:29], v6 offset:272
	ds_read_b128 v[30:33], v6 offset:528
	ds_read_u16 v34, v7 offset:16
	v_fma_mix_f32 v14, v10, v74, 0 op_sel:[0,0,0] op_sel_hi:[0,1,0]
	v_fma_mix_f32 v15, v12, v75, 0 op_sel:[0,0,0] op_sel_hi:[0,1,0]
	v_fma_mix_f32 v14, v11, v74, v14 op_sel:[0,1,0] op_sel_hi:[0,1,0]
	v_fma_mix_f32 v15, v13, v75, v15 op_sel:[0,1,0] op_sel_hi:[0,1,0]
	v_fma_mix_f32 v61, v10, v44, 0 op_sel:[0,0,0] op_sel_hi:[0,1,0]
	v_fma_mix_f32 v16, v10, v72, 0 op_sel:[0,0,0] op_sel_hi:[0,1,0]
	v_add_f32_e32 v20, v14, v15
	v_fma_mix_f32 v61, v11, v44, v61 op_sel:[0,1,0] op_sel_hi:[0,1,0]
	v_fma_mix_f32 v17, v11, v72, 0 op_sel:[0,1,0] op_sel_hi:[0,1,0]
	v_add_f32_dpp v20, v20, v20 quad_perm:[1,0,3,2] row_mask:0xf bank_mask:0xf bound_ctrl:1
	v_fma_mix_f32 v61, v12, v45, v61 op_sel:[0,0,0] op_sel_hi:[0,1,0]
	v_fma_mix_f32 v18, v12, v73, 0 op_sel:[0,0,0] op_sel_hi:[0,1,0]
	v_add_f32_dpp v20, v20, v20 quad_perm:[2,3,0,1] row_mask:0xf bank_mask:0xf bound_ctrl:1
	v_fma_mix_f32 v61, v13, v45, v61 op_sel:[0,1,0] op_sel_hi:[0,1,0]
	v_fma_mix_f32 v19, v13, v73, 0 op_sel:[0,1,0] op_sel_hi:[0,1,0]
	v_add_f32_dpp v20, v20, v20 row_half_mirror row_mask:0xf bank_mask:0xf bound_ctrl:1
	v_fma_mix_f32 v16, v82, v78, v16 op_sel:[0,0,0] op_sel_hi:[1,1,0]
	v_fma_mix_f32 v17, v82, v78, v17 op_sel:[0,1,0] op_sel_hi:[1,1,0]
	v_add_f32_dpp v20, v20, v20 row_mirror row_mask:0xf bank_mask:0xf bound_ctrl:1
	v_fma_mix_f32 v18, v82, v79, v18 op_sel:[0,0,0] op_sel_hi:[1,1,0]
	v_fma_mix_f32 v19, v82, v79, v19 op_sel:[0,1,0] op_sel_hi:[1,1,0]
	v_fma_mix_f32 v10, v20, v76, v16 op_sel:[0,0,0] op_sel_hi:[0,1,0]
	v_fma_mix_f32 v11, v20, v76, v17 op_sel:[0,1,0] op_sel_hi:[0,1,0]
	v_fma_mix_f32 v12, v20, v77, v18 op_sel:[0,0,0] op_sel_hi:[0,1,0]
	v_fma_mix_f32 v13, v20, v77, v19 op_sel:[0,1,0] op_sel_hi:[0,1,0]
	s_waitcnt lgkmcnt(4)
	ds_read_b64 v[36:37], v6 offset:1040
	ds_read_b128 v[38:41], v6 offset:1296
	ds_read_b128 v[42:45], v6 offset:1552
	ds_read_u16 v46, v7 offset:1040
	v_fma_mix_f32 v14, v10, v86, 0 op_sel:[0,0,0] op_sel_hi:[0,1,0]
	v_fma_mix_f32 v15, v12, v87, 0 op_sel:[0,0,0] op_sel_hi:[0,1,0]
	v_fma_mix_f32 v14, v11, v86, v14 op_sel:[0,1,0] op_sel_hi:[0,1,0]
	v_fma_mix_f32 v15, v13, v87, v15 op_sel:[0,1,0] op_sel_hi:[0,1,0]
	v_fma_mix_f32 v62, v10, v80, 0 op_sel:[0,0,0] op_sel_hi:[0,1,0]
	v_fma_mix_f32 v16, v10, v84, 0 op_sel:[0,0,0] op_sel_hi:[0,1,0]
	v_add_f32_e32 v20, v14, v15
	v_fma_mix_f32 v62, v11, v80, v62 op_sel:[0,1,0] op_sel_hi:[0,1,0]
	v_fma_mix_f32 v17, v11, v84, 0 op_sel:[0,1,0] op_sel_hi:[0,1,0]
	v_add_f32_dpp v20, v20, v20 quad_perm:[1,0,3,2] row_mask:0xf bank_mask:0xf bound_ctrl:1
	v_fma_mix_f32 v62, v12, v81, v62 op_sel:[0,0,0] op_sel_hi:[0,1,0]
	v_fma_mix_f32 v18, v12, v85, 0 op_sel:[0,0,0] op_sel_hi:[0,1,0]
	v_add_f32_dpp v20, v20, v20 quad_perm:[2,3,0,1] row_mask:0xf bank_mask:0xf bound_ctrl:1
	v_fma_mix_f32 v62, v13, v81, v62 op_sel:[0,1,0] op_sel_hi:[0,1,0]
	v_fma_mix_f32 v19, v13, v85, 0 op_sel:[0,1,0] op_sel_hi:[0,1,0]
	v_add_f32_dpp v20, v20, v20 row_half_mirror row_mask:0xf bank_mask:0xf bound_ctrl:1
	v_fma_mix_f32 v16, v94, v90, v16 op_sel:[0,0,0] op_sel_hi:[1,1,0]
	v_fma_mix_f32 v17, v94, v90, v17 op_sel:[0,1,0] op_sel_hi:[1,1,0]
	v_add_f32_dpp v20, v20, v20 row_mirror row_mask:0xf bank_mask:0xf bound_ctrl:1
	v_fma_mix_f32 v18, v94, v91, v18 op_sel:[0,0,0] op_sel_hi:[1,1,0]
	v_fma_mix_f32 v19, v94, v91, v19 op_sel:[0,1,0] op_sel_hi:[1,1,0]
	v_fma_mix_f32 v10, v20, v88, v16 op_sel:[0,0,0] op_sel_hi:[0,1,0]
	v_fma_mix_f32 v11, v20, v88, v17 op_sel:[0,1,0] op_sel_hi:[0,1,0]
	v_fma_mix_f32 v12, v20, v89, v18 op_sel:[0,0,0] op_sel_hi:[0,1,0]
	v_fma_mix_f32 v13, v20, v89, v19 op_sel:[0,1,0] op_sel_hi:[0,1,0]
	s_waitcnt lgkmcnt(4)
	s_add_u32 s15, s15, 1
	s_add_u32 s14, s14, 1
	v_mov_b32_e32 v69, s15
	ds_write_b32 v68, v69
	s_cmp_lt_u32 s14, 0x100
	s_cbranch_scc1 .Lrw_blk_d0
; DEVINL u16 f2bf(float a) { return (u16)(pk2(a, 0.f) & 0xffffu); }
; template <int DIR>
; DEVINL void rwkv_scan_dir(const Params& p, int task, int lane, int wave) {
;     ...
;   {
;     const float ylast = allred16(ypart);
;     ykeep = (seg == 15) ? ylast : ykeep;
;     const int q0 = 4096 - 16 + seg; yo[(long)(DIR ? (4095 - q0) : q0) * 1024] = f2bf(ykeep);
;   }
;   asm volatile("s_waitcnt vmcnt(0)" ::: "memory");
	v_fma_mix_f32 v21, v10, v92, 0 op_sel:[0,0,0] op_sel_hi:[0,1,0]
	v_fma_mix_f32 v22, v12, v93, 0 op_sel:[0,0,0] op_sel_hi:[0,1,0]
	v_fma_mix_f32 v21, v11, v92, v21 op_sel:[0,1,0] op_sel_hi:[0,1,0]
	v_fma_mix_f32 v22, v13, v93, v22 op_sel:[0,1,0] op_sel_hi:[0,1,0]
	v_add_f32_e32 v63, v21, v22
	s_nop 1
	v_add_f32_dpp v48, v48, v48 row_ror:8 row_mask:0xf bank_mask:0x3
	v_add_f32_dpp v49, v49, v49 row_ror:8 row_mask:0xf bank_mask:0x3
	v_add_f32_dpp v50, v50, v50 row_ror:8 row_mask:0xf bank_mask:0x3
	v_add_f32_dpp v51, v51, v51 row_ror:8 row_mask:0xf bank_mask:0x3
	v_add_f32_dpp v52, v52, v52 row_ror:8 row_mask:0xf bank_mask:0x3
	v_add_f32_dpp v53, v53, v53 row_ror:8 row_mask:0xf bank_mask:0x3
	v_add_f32_dpp v54, v54, v54 row_ror:8 row_mask:0xf bank_mask:0x3
	v_add_f32_dpp v55, v55, v55 row_ror:8 row_mask:0xf bank_mask:0x3
	v_add_f32_dpp v48, v56, v56 row_ror:8 row_mask:0xf bank_mask:0xc
	v_add_f32_dpp v49, v57, v57 row_ror:8 row_mask:0xf bank_mask:0xc
	v_add_f32_dpp v50, v58, v58 row_ror:8 row_mask:0xf bank_mask:0xc
	v_add_f32_dpp v51, v59, v59 row_ror:8 row_mask:0xf bank_mask:0xc
	v_add_f32_dpp v52, v60, v60 row_ror:8 row_mask:0xf bank_mask:0xc
	v_add_f32_dpp v53, v61, v61 row_ror:8 row_mask:0xf bank_mask:0xc
	v_add_f32_dpp v54, v62, v62 row_ror:8 row_mask:0xf bank_mask:0xc
	v_add_f32_dpp v55, v63, v63 row_ror:8 row_mask:0xf bank_mask:0xc
	v_add_f32_dpp v48, v48, v48 row_ror:12 row_mask:0xf bank_mask:0x5
	v_add_f32_dpp v49, v49, v49 row_ror:12 row_mask:0xf bank_mask:0x5
	v_add_f32_dpp v50, v50, v50 row_ror:12 row_mask:0xf bank_mask:0x5
	v_add_f32_dpp v51, v51, v51 row_ror:12 row_mask:0xf bank_mask:0x5
	v_add_f32_dpp v48, v52, v52 row_ror:4 row_mask:0xf bank_mask:0xa
	v_add_f32_dpp v49, v53, v53 row_ror:4 row_mask:0xf bank_mask:0xa
	v_add_f32_dpp v50, v54, v54 row_ror:4 row_mask:0xf bank_mask:0xa
	v_add_f32_dpp v51, v55, v55 row_ror:4 row_mask:0xf bank_mask:0xa
	v_add_f32_dpp v64, v48, v48 quad_perm:[2,3,0,1] row_mask:0xf bank_mask:0xf bound_ctrl:1
	v_add_f32_dpp v65, v50, v50 quad_perm:[2,3,0,1] row_mask:0xf bank_mask:0xf bound_ctrl:1
	v_cndmask_b32_e64 v56, v64, v65, s[50:51]
	v_add_f32_dpp v64, v49, v49 quad_perm:[2,3,0,1] row_mask:0xf bank_mask:0xf bound_ctrl:1
	v_add_f32_dpp v65, v51, v51 quad_perm:[2,3,0,1] row_mask:0xf bank_mask:0xf bound_ctrl:1
	v_cndmask_b32_e64 v57, v64, v65, s[50:51]
	v_add_f32_dpp v64, v56, v56 quad_perm:[1,0,3,2] row_mask:0xf bank_mask:0xf bound_ctrl:1
	s_nop 0
	v_add_f32_dpp v65, v57, v57 quad_perm:[1,0,3,2] row_mask:0xf bank_mask:0xf bound_ctrl:1
	v_cndmask_b32_e64 v66, v64, v65, s[48:49]
	v_cvt_pk_bf16_f32 v66, v66, v66
	global_store_short v8, v66, s[12:13]
	s_add_u32 s12, s12, 0x8000
	s_addc_u32 s13, s13, 0
	s_branch .Lrw_next

; DEVINL u16 f2bf(float a) { return (u16)(pk2(a, 0.f) & 0xffffu); }
; template <int DIR>
; DEVINL void rwkv_scan_dir(const Params& p, int task, int lane, int wave) {
;     ...
;     if (st > 0) { const int q0 = st - 16 + seg; yo[(long)(DIR ? (4095 - q0) : q0) * 1024] = f2bf(ykeep); }
.Lrw_ready_d1:
	s_add_u32 s3, s40, s41
	s_and_b32 s3, s3, 0x1ffff
	s_add_u32 s3, s3, 16
	s_mov_b32 m0, s3
	s_nop 0
	global_load_lds_dwordx4 v5, s[10:11] offset:0
	global_load_lds_dwordx4 v5, s[10:11] offset:1024
	global_load_lds_dwordx4 v5, s[10:11] offset:2048
	global_load_lds_dwordx4 v5, s[10:11] offset:3072
	s_sub_u32 s10, s10, 0x4000
	s_subb_u32 s11, s11, 0
	s_sub_u32 s41, s41, 0x4000
	s_and_b32 s41, s41, 0x1ffff
	ds_read_b64 v[72:73], v6 offset:13336
	ds_read_b128 v[74:77], v6 offset:13584
	ds_read_b128 v[78:81], v6 offset:13840
	ds_read_u16 v82, v7 offset:13328
	v_fma_mix_f32 v14, v10, v26, 0 op_sel:[0,0,0] op_sel_hi:[0,1,0]
	v_fma_mix_f32 v15, v12, v27, 0 op_sel:[0,0,0] op_sel_hi:[0,1,0]
	v_fma_mix_f32 v14, v11, v26, v14 op_sel:[0,1,0] op_sel_hi:[0,1,0]
	v_fma_mix_f32 v15, v13, v27, v15 op_sel:[0,1,0] op_sel_hi:[0,1,0]
	v_fma_mix_f32 v63, v10, v92, 0 op_sel:[0,0,0] op_sel_hi:[0,1,0]
	v_fma_mix_f32 v16, v10, v24, 0 op_sel:[0,0,0] op_sel_hi:[0,1,0]
	v_add_f32_e32 v20, v14, v15
	v_fma_mix_f32 v63, v11, v92, v63 op_sel:[0,1,0] op_sel_hi:[0,1,0]
	v_fma_mix_f32 v17, v11, v24, 0 op_sel:[0,1,0] op_sel_hi:[0,1,0]
	v_add_f32_dpp v20, v20, v20 quad_perm:[1,0,3,2] row_mask:0xf bank_mask:0xf bound_ctrl:1
	v_fma_mix_f32 v63, v12, v93, v63 op_sel:[0,0,0] op_sel_hi:[0,1,0]
	v_fma_mix_f32 v18, v12, v25, 0 op_sel:[0,0,0] op_sel_hi:[0,1,0]
	v_add_f32_dpp v20, v20, v20 quad_perm:[2,3,0,1] row_mask:0xf bank_mask:0xf bound_ctrl:1
	v_fma_mix_f32 v63, v13, v93, v63 op_sel:[0,1,0] op_sel_hi:[0,1,0]
	v_fma_mix_f32 v19, v13, v25, 0 op_sel:[0,1,0] op_sel_hi:[0,1,0]
	v_add_f32_dpp v20, v20, v20 row_half_mirror row_mask:0xf bank_mask:0xf bound_ctrl:1
	v_fma_mix_f32 v16, v34, v30, v16 op_sel:[0,0,0] op_sel_hi:[1,1,0]
	v_fma_mix_f32 v17, v34, v30, v17 op_sel:[0,1,0] op_sel_hi:[1,1,0]
	v_add_f32_dpp v20, v20, v20 row_mirror row_mask:0xf bank_mask:0xf bound_ctrl:1
	v_fma_mix_f32 v18, v34, v31, v18 op_sel:[0,0,0] op_sel_hi:[1,1,0]
	v_fma_mix_f32 v19, v34, v31, v19 op_sel:[0,1,0] op_sel_hi:[1,1,0]
	v_fma_mix_f32 v10, v20, v28, v16 op_sel:[0,0,0] op_sel_hi:[0,1,0]
	v_fma_mix_f32 v11, v20, v28, v17 op_sel:[0,1,0] op_sel_hi:[0,1,0]
	v_fma_mix_f32 v12, v20, v29, v18 op_sel:[0,0,0] op_sel_hi:[0,1,0]
	v_fma_mix_f32 v13, v20, v29, v19 op_sel:[0,1,0] op_sel_hi:[0,1,0]
	s_waitcnt lgkmcnt(4)
	s_cmp_eq_u32 s14, 0
	s_cbranch_scc1 .Lrw_skip_d1
	v_add_f32_dpp v48, v48, v48 row_ror:8 row_mask:0xf bank_mask:0x3
	v_add_f32_dpp v49, v49, v49 row_ror:8 row_mask:0xf bank_mask:0x3
	v_add_f32_dpp v50, v50, v50 row_ror:8 row_mask:0xf bank_mask:0x3
	v_add_f32_dpp v51, v51, v51 row_ror:8 row_mask:0xf bank_mask:0x3
	v_add_f32_dpp v52, v52, v52 row_ror:8 row_mask:0xf bank_mask:0x3
	v_add_f32_dpp v53, v53, v53 row_ror:8 row_mask:0xf bank_mask:0x3
	v_add_f32_dpp v54, v54, v54 row_ror:8 row_mask:0xf bank_mask:0x3
	v_add_f32_dpp v55, v55, v55 row_ror:8 row_mask:0xf bank_mask:0x3
	v_add_f32_dpp v48, v56, v56 row_ror:8 row_mask:0xf bank_mask:0xc
	v_add_f32_dpp v49, v57, v57 row_ror:8 row_mask:0xf bank_mask:0xc
	v_add_f32_dpp v50, v58, v58 row_ror:8 row_mask:0xf bank_mask:0xc
	v_add_f32_dpp v51, v59, v59 row_ror:8 row_mask:0xf bank_mask:0xc
	v_add_f32_dpp v52, v60, v60 row_ror:8 row_mask:0xf bank_mask:0xc
	v_add_f32_dpp v53, v61, v61 row_ror:8 row_mask:0xf bank_mask:0xc
	v_add_f32_dpp v54, v62, v62 row_ror:8 row_mask:0xf bank_mask:0xc
	v_add_f32_dpp v55, v63, v63 row_ror:8 row_mask:0xf bank_mask:0xc
	v_add_f32_dpp v48, v48, v48 row_ror:12 row_mask:0xf bank_mask:0x5
	v_add_f32_dpp v49, v49, v49 row_ror:12 row_mask:0xf bank_mask:0x5
	v_add_f32_dpp v50, v50, v50 row_ror:12 row_mask:0xf bank_mask:0x5
	v_add_f32_dpp v51, v51, v51 row_ror:12 row_mask:0xf bank_mask:0x5
	v_add_f32_dpp v48, v52, v52 row_ror:4 row_mask:0xf bank_mask:0xa
	v_add_f32_dpp v49, v53, v53 row_ror:4 row_mask:0xf bank_mask:0xa
	v_add_f32_dpp v50, v54, v54 row_ror:4 row_mask:0xf bank_mask:0xa
	v_add_f32_dpp v51, v55, v55 row_ror:4 row_mask:0xf bank_mask:0xa
	v_add_f32_dpp v64, v48, v48 quad_perm:[2,3,0,1] row_mask:0xf bank_mask:0xf bound_ctrl:1
	v_add_f32_dpp v65, v50, v50 quad_perm:[2,3,0,1] row_mask:0xf bank_mask:0xf bound_ctrl:1
	v_cndmask_b32_e64 v56, v64, v65, s[50:51]
	v_add_f32_dpp v64, v49, v49 quad_perm:[2,3,0,1] row_mask:0xf bank_mask:0xf bound_ctrl:1
	v_add_f32_dpp v65, v51, v51 quad_perm:[2,3,0,1] row_mask:0xf bank_mask:0xf bound_ctrl:1
	v_cndmask_b32_e64 v57, v64, v65, s[50:51]
	v_add_f32_dpp v64, v56, v56 quad_perm:[1,0,3,2] row_mask:0xf bank_mask:0xf bound_ctrl:1
	s_nop 0
	v_add_f32_dpp v65, v57, v57 quad_perm:[1,0,3,2] row_mask:0xf bank_mask:0xf bound_ctrl:1
	v_cndmask_b32_e64 v66, v64, v65, s[48:49]
	v_cvt_pk_bf16_f32 v66, v66, v66
	global_store_short v8, v66, s[12:13]
	s_sub_u32 s12, s12, 0x8000
	s_subb_u32 s13, s13, 0
.Lrw_skip_d1:
	ds_read_b64 v[84:85], v6 offset:12312
	ds_read_b128 v[86:89], v6 offset:12560
	ds_read_b128 v[90:93], v6 offset:12816
	ds_read_u16 v94, v7 offset:12304
	v_fma_mix_f32 v14, v10, v38, 0 op_sel:[0,0,0] op_sel_hi:[0,1,0]
	v_fma_mix_f32 v15, v12, v39, 0 op_sel:[0,0,0] op_sel_hi:[0,1,0]
	v_fma_mix_f32 v14, v11, v38, v14 op_sel:[0,1,0] op_sel_hi:[0,1,0]
	v_fma_mix_f32 v15, v13, v39, v15 op_sel:[0,1,0] op_sel_hi:[0,1,0]
	v_fma_mix_f32 v48, v10, v32, 0 op_sel:[0,0,0] op_sel_hi:[0,1,0]
	v_fma_mix_f32 v16, v10, v36, 0 op_sel:[0,0,0] op_sel_hi:[0,1,0]
	v_add_f32_e32 v20, v14, v15
	v_fma_mix_f32 v48, v11, v32, v48 op_sel:[0,1,0] op_sel_hi:[0,1,0]
	v_fma_mix_f32 v17, v11, v36, 0 op_sel:[0,1,0] op_sel_hi:[0,1,0]
	v_add_f32_dpp v20, v20, v20 quad_perm:[1,0,3,2] row_mask:0xf bank_mask:0xf bound_ctrl:1
	v_fma_mix_f32 v48, v12, v33, v48 op_sel:[0,0,0] op_sel_hi:[0,1,0]
	v_fma_mix_f32 v18, v12, v37, 0 op_sel:[0,0,0] op_sel_hi:[0,1,0]
	v_add_f32_dpp v20, v20, v20 quad_perm:[2,3,0,1] row_mask:0xf bank_mask:0xf bound_ctrl:1
	v_fma_mix_f32 v48, v13, v33, v48 op_sel:[0,1,0] op_sel_hi:[0,1,0]
	v_fma_mix_f32 v19, v13, v37, 0 op_sel:[0,1,0] op_sel_hi:[0,1,0]
	v_add_f32_dpp v20, v20, v20 row_half_mirror row_mask:0xf bank_mask:0xf bound_ctrl:1
	v_fma_mix_f32 v16, v46, v42, v16 op_sel:[0,0,0] op_sel_hi:[1,1,0]
	v_fma_mix_f32 v17, v46, v42, v17 op_sel:[0,1,0] op_sel_hi:[1,1,0]
	v_add_f32_dpp v20, v20, v20 row_mirror row_mask:0xf bank_mask:0xf bound_ctrl:1
	v_fma_mix_f32 v18, v46, v43, v18 op_sel:[0,0,0] op_sel_hi:[1,1,0]
	v_fma_mix_f32 v19, v46, v43, v19 op_sel:[0,1,0] op_sel_hi:[1,1,0]
	v_fma_mix_f32 v10, v20, v40, v16 op_sel:[0,0,0] op_sel_hi:[0,1,0]
	v_fma_mix_f32 v11, v20, v40, v17 op_sel:[0,1,0] op_sel_hi:[0,1,0]
	v_fma_mix_f32 v12, v20, v41, v18 op_sel:[0,0,0] op_sel_hi:[0,1,0]
	v_fma_mix_f32 v13, v20, v41, v19 op_sel:[0,1,0] op_sel_hi:[0,1,0]
	s_waitcnt lgkmcnt(4)
	ds_read_b64 v[24:25], v6 offset:11288
	ds_read_b128 v[26:29], v6 offset:11536
	ds_read_b128 v[30:33], v6 offset:11792
	ds_read_u16 v34, v7 offset:11280
	v_fma_mix_f32 v14, v10, v74, 0 op_sel:[0,0,0] op_sel_hi:[0,1,0]
	v_fma_mix_f32 v15, v12, v75, 0 op_sel:[0,0,0] op_sel_hi:[0,1,0]
	v_fma_mix_f32 v14, v11, v74, v14 op_sel:[0,1,0] op_sel_hi:[0,1,0]
	v_fma_mix_f32 v15, v13, v75, v15 op_sel:[0,1,0] op_sel_hi:[0,1,0]
	v_fma_mix_f32 v49, v10, v44, 0 op_sel:[0,0,0] op_sel_hi:[0,1,0]
	v_fma_mix_f32 v16, v10, v72, 0 op_sel:[0,0,0] op_sel_hi:[0,1,0]
	v_add_f32_e32 v20, v14, v15
	v_fma_mix_f32 v49, v11, v44, v49 op_sel:[0,1,0] op_sel_hi:[0,1,0]
	v_fma_mix_f32 v17, v11, v72, 0 op_sel:[0,1,0] op_sel_hi:[0,1,0]
	v_add_f32_dpp v20, v20, v20 quad_perm:[1,0,3,2] row_mask:0xf bank_mask:0xf bound_ctrl:1
	v_fma_mix_f32 v49, v12, v45, v49 op_sel:[0,0,0] op_sel_hi:[0,1,0]
	v_fma_mix_f32 v18, v12, v73, 0 op_sel:[0,0,0] op_sel_hi:[0,1,0]
	v_add_f32_dpp v20, v20, v20 quad_perm:[2,3,0,1] row_mask:0xf bank_mask:0xf bound_ctrl:1
	v_fma_mix_f32 v49, v13, v45, v49 op_sel:[0,1,0] op_sel_hi:[0,1,0]
	v_fma_mix_f32 v19, v13, v73, 0 op_sel:[0,1,0] op_sel_hi:[0,1,0]
	v_add_f32_dpp v20, v20, v20 row_half_mirror row_mask:0xf bank_mask:0xf bound_ctrl:1
	v_fma_mix_f32 v16, v82, v78, v16 op_sel:[0,0,0] op_sel_hi:[1,1,0]
	v_fma_mix_f32 v17, v82, v78, v17 op_sel:[0,1,0] op_sel_hi:[1,1,0]
	v_add_f32_dpp v20, v20, v20 row_mirror row_mask:0xf bank_mask:0xf bound_ctrl:1
	v_fma_mix_f32 v18, v82, v79, v18 op_sel:[0,0,0] op_sel_hi:[1,1,0]
	v_fma_mix_f32 v19, v82, v79, v19 op_sel:[0,1,0] op_sel_hi:[1,1,0]
	v_fma_mix_f32 v10, v20, v76, v16 op_sel:[0,0,0] op_sel_hi:[0,1,0]
	v_fma_mix_f32 v11, v20, v76, v17 op_sel:[0,1,0] op_sel_hi:[0,1,0]
	v_fma_mix_f32 v12, v20, v77, v18 op_sel:[0,0,0] op_sel_hi:[0,1,0]
	v_fma_mix_f32 v13, v20, v77, v19 op_sel:[0,1,0] op_sel_hi:[0,1,0]
	s_waitcnt lgkmcnt(4)
	ds_read_b64 v[36:37], v6 offset:10264
	ds_read_b128 v[38:41], v6 offset:10512
	ds_read_b128 v[42:45], v6 offset:10768
	ds_read_u16 v46, v7 offset:10256
	v_fma_mix_f32 v14, v10, v86, 0 op_sel:[0,0,0] op_sel_hi:[0,1,0]
	v_fma_mix_f32 v15, v12, v87, 0 op_sel:[0,0,0] op_sel_hi:[0,1,0]
	v_fma_mix_f32 v14, v11, v86, v14 op_sel:[0,1,0] op_sel_hi:[0,1,0]
	v_fma_mix_f32 v15, v13, v87, v15 op_sel:[0,1,0] op_sel_hi:[0,1,0]
	v_fma_mix_f32 v50, v10, v80, 0 op_sel:[0,0,0] op_sel_hi:[0,1,0]
	v_fma_mix_f32 v16, v10, v84, 0 op_sel:[0,0,0] op_sel_hi:[0,1,0]
	v_add_f32_e32 v20, v14, v15
	v_fma_mix_f32 v50, v11, v80, v50 op_sel:[0,1,0] op_sel_hi:[0,1,0]
	v_fma_mix_f32 v17, v11, v84, 0 op_sel:[0,1,0] op_sel_hi:[0,1,0]
	v_add_f32_dpp v20, v20, v20 quad_perm:[1,0,3,2] row_mask:0xf bank_mask:0xf bound_ctrl:1
	v_fma_mix_f32 v50, v12, v81, v50 op_sel:[0,0,0] op_sel_hi:[0,1,0]
	v_fma_mix_f32 v18, v12, v85, 0 op_sel:[0,0,0] op_sel_hi:[0,1,0]
	v_add_f32_dpp v20, v20, v20 quad_perm:[2,3,0,1] row_mask:0xf bank_mask:0xf bound_ctrl:1
	v_fma_mix_f32 v50, v13, v81, v50 op_sel:[0,1,0] op_sel_hi:[0,1,0]
	v_fma_mix_f32 v19, v13, v85, 0 op_sel:[0,1,0] op_sel_hi:[0,1,0]
	v_add_f32_dpp v20, v20, v20 row_half_mirror row_mask:0xf bank_mask:0xf bound_ctrl:1
	v_fma_mix_f32 v16, v94, v90, v16 op_sel:[0,0,0] op_sel_hi:[1,1,0]
	v_fma_mix_f32 v17, v94, v90, v17 op_sel:[0,1,0] op_sel_hi:[1,1,0]
	v_add_f32_dpp v20, v20, v20 row_mirror row_mask:0xf bank_mask:0xf bound_ctrl:1
	v_fma_mix_f32 v18, v94, v91, v18 op_sel:[0,0,0] op_sel_hi:[1,1,0]
	v_fma_mix_f32 v19, v94, v91, v19 op_sel:[0,1,0] op_sel_hi:[1,1,0]
	v_fma_mix_f32 v10, v20, v88, v16 op_sel:[0,0,0] op_sel_hi:[0,1,0]
	v_fma_mix_f32 v11, v20, v88, v17 op_sel:[0,1,0] op_sel_hi:[0,1,0]
	v_fma_mix_f32 v12, v20, v89, v18 op_sel:[0,0,0] op_sel_hi:[0,1,0]
	v_fma_mix_f32 v13, v20, v89, v19 op_sel:[0,1,0] op_sel_hi:[0,1,0]
	s_waitcnt lgkmcnt(4)
	ds_read_b64 v[72:73], v6 offset:9240
	ds_read_b128 v[74:77], v6 offset:9488
	ds_read_b128 v[78:81], v6 offset:9744
	ds_read_u16 v82, v7 offset:9232
	v_fma_mix_f32 v14, v10, v26, 0 op_sel:[0,0,0] op_sel_hi:[0,1,0]
	v_fma_mix_f32 v15, v12, v27, 0 op_sel:[0,0,0] op_sel_hi:[0,1,0]
	v_fma_mix_f32 v14, v11, v26, v14 op_sel:[0,1,0] op_sel_hi:[0,1,0]
	v_fma_mix_f32 v15, v13, v27, v15 op_sel:[0,1,0] op_sel_hi:[0,1,0]
	v_fma_mix_f32 v51, v10, v92, 0 op_sel:[0,0,0] op_sel_hi:[0,1,0]
	v_fma_mix_f32 v16, v10, v24, 0 op_sel:[0,0,0] op_sel_hi:[0,1,0]
	v_add_f32_e32 v20, v14, v15
	v_fma_mix_f32 v51, v11, v92, v51 op_sel:[0,1,0] op_sel_hi:[0,1,0]
	v_fma_mix_f32 v17, v11, v24, 0 op_sel:[0,1,0] op_sel_hi:[0,1,0]
	v_add_f32_dpp v20, v20, v20 quad_perm:[1,0,3,2] row_mask:0xf bank_mask:0xf bound_ctrl:1
	v_fma_mix_f32 v51, v12, v93, v51 op_sel:[0,0,0] op_sel_hi:[0,1,0]
	v_fma_mix_f32 v18, v12, v25, 0 op_sel:[0,0,0] op_sel_hi:[0,1,0]
	v_add_f32_dpp v20, v20, v20 quad_perm:[2,3,0,1] row_mask:0xf bank_mask:0xf bound_ctrl:1
	v_fma_mix_f32 v51, v13, v93, v51 op_sel:[0,1,0] op_sel_hi:[0,1,0]
	v_fma_mix_f32 v19, v13, v25, 0 op_sel:[0,1,0] op_sel_hi:[0,1,0]
	v_add_f32_dpp v20, v20, v20 row_half_mirror row_mask:0xf bank_mask:0xf bound_ctrl:1
	v_fma_mix_f32 v16, v34, v30, v16 op_sel:[0,0,0] op_sel_hi:[1,1,0]
	v_fma_mix_f32 v17, v34, v30, v17 op_sel:[0,1,0] op_sel_hi:[1,1,0]
	v_add_f32_dpp v20, v20, v20 row_mirror row_mask:0xf bank_mask:0xf bound_ctrl:1
	v_fma_mix_f32 v18, v34, v31, v18 op_sel:[0,0,0] op_sel_hi:[1,1,0]
	v_fma_mix_f32 v19, v34, v31, v19 op_sel:[0,1,0] op_sel_hi:[1,1,0]
	v_fma_mix_f32 v10, v20, v28, v16 op_sel:[0,0,0] op_sel_hi:[0,1,0]
	v_fma_mix_f32 v11, v20, v28, v17 op_sel:[0,1,0] op_sel_hi:[0,1,0]
	v_fma_mix_f32 v12, v20, v29, v18 op_sel:[0,0,0] op_sel_hi:[0,1,0]
	v_fma_mix_f32 v13, v20, v29, v19 op_sel:[0,1,0] op_sel_hi:[0,1,0]
	s_waitcnt lgkmcnt(4)
	ds_read_b64 v[84:85], v6 offset:8216
	ds_read_b128 v[86:89], v6 offset:8464
	ds_read_b128 v[90:93], v6 offset:8720
	ds_read_u16 v94, v7 offset:8208
	v_fma_mix_f32 v14, v10, v38, 0 op_sel:[0,0,0] op_sel_hi:[0,1,0]
	v_fma_mix_f32 v15, v12, v39, 0 op_sel:[0,0,0] op_sel_hi:[0,1,0]
	v_fma_mix_f32 v14, v11, v38, v14 op_sel:[0,1,0] op_sel_hi:[0,1,0]
	v_fma_mix_f32 v15, v13, v39, v15 op_sel:[0,1,0] op_sel_hi:[0,1,0]
	v_fma_mix_f32 v52, v10, v32, 0 op_sel:[0,0,0] op_sel_hi:[0,1,0]
	v_fma_mix_f32 v16, v10, v36, 0 op_sel:[0,0,0] op_sel_hi:[0,1,0]
	v_add_f32_e32 v20, v14, v15
	v_fma_mix_f32 v52, v11, v32, v52 op_sel:[0,1,0] op_sel_hi:[0,1,0]
	v_fma_mix_f32 v17, v11, v36, 0 op_sel:[0,1,0] op_sel_hi:[0,1,0]
	v_add_f32_dpp v20, v20, v20 quad_perm:[1,0,3,2] row_mask:0xf bank_mask:0xf bound_ctrl:1
	v_fma_mix_f32 v52, v12, v33, v52 op_sel:[0,0,0] op_sel_hi:[0,1,0]
	v_fma_mix_f32 v18, v12, v37, 0 op_sel:[0,0,0] op_sel_hi:[0,1,0]
	v_add_f32_dpp v20, v20, v20 quad_perm:[2,3,0,1] row_mask:0xf bank_mask:0xf bound_ctrl:1
	v_fma_mix_f32 v52, v13, v33, v52 op_sel:[0,1,0] op_sel_hi:[0,1,0]
	v_fma_mix_f32 v19, v13, v37, 0 op_sel:[0,1,0] op_sel_hi:[0,1,0]
	v_add_f32_dpp v20, v20, v20 row_half_mirror row_mask:0xf bank_mask:0xf bound_ctrl:1
	v_fma_mix_f32 v16, v46, v42, v16 op_sel:[0,0,0] op_sel_hi:[1,1,0]
	v_fma_mix_f32 v17, v46, v42, v17 op_sel:[0,1,0] op_sel_hi:[1,1,0]
	v_add_f32_dpp v20, v20, v20 row_mirror row_mask:0xf bank_mask:0xf bound_ctrl:1
	v_fma_mix_f32 v18, v46, v43, v18 op_sel:[0,0,0] op_sel_hi:[1,1,0]
	v_fma_mix_f32 v19, v46, v43, v19 op_sel:[0,1,0] op_sel_hi:[1,1,0]
	v_fma_mix_f32 v10, v20, v40, v16 op_sel:[0,0,0] op_sel_hi:[0,1,0]
	v_fma_mix_f32 v11, v20, v40, v17 op_sel:[0,1,0] op_sel_hi:[0,1,0]
	v_fma_mix_f32 v12, v20, v41, v18 op_sel:[0,0,0] op_sel_hi:[0,1,0]
	v_fma_mix_f32 v13, v20, v41, v19 op_sel:[0,1,0] op_sel_hi:[0,1,0]
	s_waitcnt lgkmcnt(4)
	ds_read_b64 v[24:25], v6 offset:7192
	ds_read_b128 v[26:29], v6 offset:7440
	ds_read_b128 v[30:33], v6 offset:7696
	ds_read_u16 v34, v7 offset:7184
	v_fma_mix_f32 v14, v10, v74, 0 op_sel:[0,0,0] op_sel_hi:[0,1,0]
	v_fma_mix_f32 v15, v12, v75, 0 op_sel:[0,0,0] op_sel_hi:[0,1,0]
	v_fma_mix_f32 v14, v11, v74, v14 op_sel:[0,1,0] op_sel_hi:[0,1,0]
	v_fma_mix_f32 v15, v13, v75, v15 op_sel:[0,1,0] op_sel_hi:[0,1,0]
	v_fma_mix_f32 v53, v10, v44, 0 op_sel:[0,0,0] op_sel_hi:[0,1,0]
	v_fma_mix_f32 v16, v10, v72, 0 op_sel:[0,0,0] op_sel_hi:[0,1,0]
	v_add_f32_e32 v20, v14, v15
	v_fma_mix_f32 v53, v11, v44, v53 op_sel:[0,1,0] op_sel_hi:[0,1,0]
	v_fma_mix_f32 v17, v11, v72, 0 op_sel:[0,1,0] op_sel_hi:[0,1,0]
	v_add_f32_dpp v20, v20, v20 quad_perm:[1,0,3,2] row_mask:0xf bank_mask:0xf bound_ctrl:1
	v_fma_mix_f32 v53, v12, v45, v53 op_sel:[0,0,0] op_sel_hi:[0,1,0]
	v_fma_mix_f32 v18, v12, v73, 0 op_sel:[0,0,0] op_sel_hi:[0,1,0]
	v_add_f32_dpp v20, v20, v20 quad_perm:[2,3,0,1] row_mask:0xf bank_mask:0xf bound_ctrl:1
	v_fma_mix_f32 v53, v13, v45, v53 op_sel:[0,1,0] op_sel_hi:[0,1,0]
	v_fma_mix_f32 v19, v13, v73, 0 op_sel:[0,1,0] op_sel_hi:[0,1,0]
	v_add_f32_dpp v20, v20, v20 row_half_mirror row_mask:0xf bank_mask:0xf bound_ctrl:1
	v_fma_mix_f32 v16, v82, v78, v16 op_sel:[0,0,0] op_sel_hi:[1,1,0]
	v_fma_mix_f32 v17, v82, v78, v17 op_sel:[0,1,0] op_sel_hi:[1,1,0]
	v_add_f32_dpp v20, v20, v20 row_mirror row_mask:0xf bank_mask:0xf bound_ctrl:1
	v_fma_mix_f32 v18, v82, v79, v18 op_sel:[0,0,0] op_sel_hi:[1,1,0]
	v_fma_mix_f32 v19, v82, v79, v19 op_sel:[0,1,0] op_sel_hi:[1,1,0]
	v_fma_mix_f32 v10, v20, v76, v16 op_sel:[0,0,0] op_sel_hi:[0,1,0]
	v_fma_mix_f32 v11, v20, v76, v17 op_sel:[0,1,0] op_sel_hi:[0,1,0]
	v_fma_mix_f32 v12, v20, v77, v18 op_sel:[0,0,0] op_sel_hi:[0,1,0]
	v_fma_mix_f32 v13, v20, v77, v19 op_sel:[0,1,0] op_sel_hi:[0,1,0]
	s_waitcnt lgkmcnt(4)
	ds_read_b64 v[36:37], v6 offset:6168
	ds_read_b128 v[38:41], v6 offset:6416
	ds_read_b128 v[42:45], v6 offset:6672
	ds_read_u16 v46, v7 offset:6160
	v_fma_mix_f32 v14, v10, v86, 0 op_sel:[0,0,0] op_sel_hi:[0,1,0]
	v_fma_mix_f32 v15, v12, v87, 0 op_sel:[0,0,0] op_sel_hi:[0,1,0]
	v_fma_mix_f32 v14, v11, v86, v14 op_sel:[0,1,0] op_sel_hi:[0,1,0]
	v_fma_mix_f32 v15, v13, v87, v15 op_sel:[0,1,0] op_sel_hi:[0,1,0]
	v_fma_mix_f32 v54, v10, v80, 0 op_sel:[0,0,0] op_sel_hi:[0,1,0]
	v_fma_mix_f32 v16, v10, v84, 0 op_sel:[0,0,0] op_sel_hi:[0,1,0]
	v_add_f32_e32 v20, v14, v15
	v_fma_mix_f32 v54, v11, v80, v54 op_sel:[0,1,0] op_sel_hi:[0,1,0]
	v_fma_mix_f32 v17, v11, v84, 0 op_sel:[0,1,0] op_sel_hi:[0,1,0]
	v_add_f32_dpp v20, v20, v20 quad_perm:[1,0,3,2] row_mask:0xf bank_mask:0xf bound_ctrl:1
	v_fma_mix_f32 v54, v12, v81, v54 op_sel:[0,0,0] op_sel_hi:[0,1,0]
	v_fma_mix_f32 v18, v12, v85, 0 op_sel:[0,0,0] op_sel_hi:[0,1,0]
	v_add_f32_dpp v20, v20, v20 quad_perm:[2,3,0,1] row_mask:0xf bank_mask:0xf bound_ctrl:1
	v_fma_mix_f32 v54, v13, v81, v54 op_sel:[0,1,0] op_sel_hi:[0,1,0]
	v_fma_mix_f32 v19, v13, v85, 0 op_sel:[0,1,0] op_sel_hi:[0,1,0]
	v_add_f32_dpp v20, v20, v20 row_half_mirror row_mask:0xf bank_mask:0xf bound_ctrl:1
	v_fma_mix_f32 v16, v94, v90, v16 op_sel:[0,0,0] op_sel_hi:[1,1,0]
	v_fma_mix_f32 v17, v94, v90, v17 op_sel:[0,1,0] op_sel_hi:[1,1,0]
	v_add_f32_dpp v20, v20, v20 row_mirror row_mask:0xf bank_mask:0xf bound_ctrl:1
	v_fma_mix_f32 v18, v94, v91, v18 op_sel:[0,0,0] op_sel_hi:[1,1,0]
	v_fma_mix_f32 v19, v94, v91, v19 op_sel:[0,1,0] op_sel_hi:[1,1,0]
	v_fma_mix_f32 v10, v20, v88, v16 op_sel:[0,0,0] op_sel_hi:[0,1,0]
	v_fma_mix_f32 v11, v20, v88, v17 op_sel:[0,1,0] op_sel_hi:[0,1,0]
	v_fma_mix_f32 v12, v20, v89, v18 op_sel:[0,0,0] op_sel_hi:[0,1,0]
	v_fma_mix_f32 v13, v20, v89, v19 op_sel:[0,1,0] op_sel_hi:[0,1,0]
	s_waitcnt lgkmcnt(4)
	ds_read_b64 v[72:73], v6 offset:5144
	ds_read_b128 v[74:77], v6 offset:5392
	ds_read_b128 v[78:81], v6 offset:5648
	ds_read_u16 v82, v7 offset:5136
	v_fma_mix_f32 v14, v10, v26, 0 op_sel:[0,0,0] op_sel_hi:[0,1,0]
	v_fma_mix_f32 v15, v12, v27, 0 op_sel:[0,0,0] op_sel_hi:[0,1,0]
	v_fma_mix_f32 v14, v11, v26, v14 op_sel:[0,1,0] op_sel_hi:[0,1,0]
	v_fma_mix_f32 v15, v13, v27, v15 op_sel:[0,1,0] op_sel_hi:[0,1,0]
	v_fma_mix_f32 v55, v10, v92, 0 op_sel:[0,0,0] op_sel_hi:[0,1,0]
	v_fma_mix_f32 v16, v10, v24, 0 op_sel:[0,0,0] op_sel_hi:[0,1,0]
	v_add_f32_e32 v20, v14, v15
	v_fma_mix_f32 v55, v11, v92, v55 op_sel:[0,1,0] op_sel_hi:[0,1,0]
	v_fma_mix_f32 v17, v11, v24, 0 op_sel:[0,1,0] op_sel_hi:[0,1,0]
	v_add_f32_dpp v20, v20, v20 quad_perm:[1,0,3,2] row_mask:0xf bank_mask:0xf bound_ctrl:1
	v_fma_mix_f32 v55, v12, v93, v55 op_sel:[0,0,0] op_sel_hi:[0,1,0]
	v_fma_mix_f32 v18, v12, v25, 0 op_sel:[0,0,0] op_sel_hi:[0,1,0]
	v_add_f32_dpp v20, v20, v20 quad_perm:[2,3,0,1] row_mask:0xf bank_mask:0xf bound_ctrl:1
	v_fma_mix_f32 v55, v13, v93, v55 op_sel:[0,1,0] op_sel_hi:[0,1,0]
	v_fma_mix_f32 v19, v13, v25, 0 op_sel:[0,1,0] op_sel_hi:[0,1,0]
	v_add_f32_dpp v20, v20, v20 row_half_mirror row_mask:0xf bank_mask:0xf bound_ctrl:1
	v_fma_mix_f32 v16, v34, v30, v16 op_sel:[0,0,0] op_sel_hi:[1,1,0]
	v_fma_mix_f32 v17, v34, v30, v17 op_sel:[0,1,0] op_sel_hi:[1,1,0]
	v_add_f32_dpp v20, v20, v20 row_mirror row_mask:0xf bank_mask:0xf bound_ctrl:1
	v_fma_mix_f32 v18, v34, v31, v18 op_sel:[0,0,0] op_sel_hi:[1,1,0]
	v_fma_mix_f32 v19, v34, v31, v19 op_sel:[0,1,0] op_sel_hi:[1,1,0]
	v_fma_mix_f32 v10, v20, v28, v16 op_sel:[0,0,0] op_sel_hi:[0,1,0]
	v_fma_mix_f32 v11, v20, v28, v17 op_sel:[0,1,0] op_sel_hi:[0,1,0]
	v_fma_mix_f32 v12, v20, v29, v18 op_sel:[0,0,0] op_sel_hi:[0,1,0]
	v_fma_mix_f32 v13, v20, v29, v19 op_sel:[0,1,0] op_sel_hi:[0,1,0]
	s_waitcnt lgkmcnt(4)
	ds_read_b64 v[84:85], v6 offset:4120
	ds_read_b128 v[86:89], v6 offset:4368
	ds_read_b128 v[90:93], v6 offset:4624
	ds_read_u16 v94, v7 offset:4112
	v_fma_mix_f32 v14, v10, v38, 0 op_sel:[0,0,0] op_sel_hi:[0,1,0]
	v_fma_mix_f32 v15, v12, v39, 0 op_sel:[0,0,0] op_sel_hi:[0,1,0]
	v_fma_mix_f32 v14, v11, v38, v14 op_sel:[0,1,0] op_sel_hi:[0,1,0]
	v_fma_mix_f32 v15, v13, v39, v15 op_sel:[0,1,0] op_sel_hi:[0,1,0]
	v_fma_mix_f32 v56, v10, v32, 0 op_sel:[0,0,0] op_sel_hi:[0,1,0]
	v_fma_mix_f32 v16, v10, v36, 0 op_sel:[0,0,0] op_sel_hi:[0,1,0]
	v_add_f32_e32 v20, v14, v15
	v_fma_mix_f32 v56, v11, v32, v56 op_sel:[0,1,0] op_sel_hi:[0,1,0]
	v_fma_mix_f32 v17, v11, v36, 0 op_sel:[0,1,0] op_sel_hi:[0,1,0]
	v_add_f32_dpp v20, v20, v20 quad_perm:[1,0,3,2] row_mask:0xf bank_mask:0xf bound_ctrl:1
	v_fma_mix_f32 v56, v12, v33, v56 op_sel:[0,0,0] op_sel_hi:[0,1,0]
	v_fma_mix_f32 v18, v12, v37, 0 op_sel:[0,0,0] op_sel_hi:[0,1,0]
	v_add_f32_dpp v20, v20, v20 quad_perm:[2,3,0,1] row_mask:0xf bank_mask:0xf bound_ctrl:1
	v_fma_mix_f32 v56, v13, v33, v56 op_sel:[0,1,0] op_sel_hi:[0,1,0]
	v_fma_mix_f32 v19, v13, v37, 0 op_sel:[0,1,0] op_sel_hi:[0,1,0]
	v_add_f32_dpp v20, v20, v20 row_half_mirror row_mask:0xf bank_mask:0xf bound_ctrl:1
	v_fma_mix_f32 v16, v46, v42, v16 op_sel:[0,0,0] op_sel_hi:[1,1,0]
	v_fma_mix_f32 v17, v46, v42, v17 op_sel:[0,1,0] op_sel_hi:[1,1,0]
	v_add_f32_dpp v20, v20, v20 row_mirror row_mask:0xf bank_mask:0xf bound_ctrl:1
	v_fma_mix_f32 v18, v46, v43, v18 op_sel:[0,0,0] op_sel_hi:[1,1,0]
	v_fma_mix_f32 v19, v46, v43, v19 op_sel:[0,1,0] op_sel_hi:[1,1,0]
	v_fma_mix_f32 v10, v20, v40, v16 op_sel:[0,0,0] op_sel_hi:[0,1,0]
	v_fma_mix_f32 v11, v20, v40, v17 op_sel:[0,1,0] op_sel_hi:[0,1,0]
	v_fma_mix_f32 v12, v20, v41, v18 op_sel:[0,0,0] op_sel_hi:[0,1,0]
	v_fma_mix_f32 v13, v20, v41, v19 op_sel:[0,1,0] op_sel_hi:[0,1,0]
	s_waitcnt lgkmcnt(4)
	ds_read_b64 v[24:25], v6 offset:3096
	ds_read_b128 v[26:29], v6 offset:3344
	ds_read_b128 v[30:33], v6 offset:3600
	ds_read_u16 v34, v7 offset:3088
	v_fma_mix_f32 v14, v10, v74, 0 op_sel:[0,0,0] op_sel_hi:[0,1,0]
	v_fma_mix_f32 v15, v12, v75, 0 op_sel:[0,0,0] op_sel_hi:[0,1,0]
	v_fma_mix_f32 v14, v11, v74, v14 op_sel:[0,1,0] op_sel_hi:[0,1,0]
	v_fma_mix_f32 v15, v13, v75, v15 op_sel:[0,1,0] op_sel_hi:[0,1,0]
	v_fma_mix_f32 v57, v10, v44, 0 op_sel:[0,0,0] op_sel_hi:[0,1,0]
	v_fma_mix_f32 v16, v10, v72, 0 op_sel:[0,0,0] op_sel_hi:[0,1,0]
	v_add_f32_e32 v20, v14, v15
	v_fma_mix_f32 v57, v11, v44, v57 op_sel:[0,1,0] op_sel_hi:[0,1,0]
	v_fma_mix_f32 v17, v11, v72, 0 op_sel:[0,1,0] op_sel_hi:[0,1,0]
	v_add_f32_dpp v20, v20, v20 quad_perm:[1,0,3,2] row_mask:0xf bank_mask:0xf bound_ctrl:1
	v_fma_mix_f32 v57, v12, v45, v57 op_sel:[0,0,0] op_sel_hi:[0,1,0]
	v_fma_mix_f32 v18, v12, v73, 0 op_sel:[0,0,0] op_sel_hi:[0,1,0]
	v_add_f32_dpp v20, v20, v20 quad_perm:[2,3,0,1] row_mask:0xf bank_mask:0xf bound_ctrl:1
	v_fma_mix_f32 v57, v13, v45, v57 op_sel:[0,1,0] op_sel_hi:[0,1,0]
	v_fma_mix_f32 v19, v13, v73, 0 op_sel:[0,1,0] op_sel_hi:[0,1,0]
	v_add_f32_dpp v20, v20, v20 row_half_mirror row_mask:0xf bank_mask:0xf bound_ctrl:1
	v_fma_mix_f32 v16, v82, v78, v16 op_sel:[0,0,0] op_sel_hi:[1,1,0]
	v_fma_mix_f32 v17, v82, v78, v17 op_sel:[0,1,0] op_sel_hi:[1,1,0]
	v_add_f32_dpp v20, v20, v20 row_mirror row_mask:0xf bank_mask:0xf bound_ctrl:1
	v_fma_mix_f32 v18, v82, v79, v18 op_sel:[0,0,0] op_sel_hi:[1,1,0]
	v_fma_mix_f32 v19, v82, v79, v19 op_sel:[0,1,0] op_sel_hi:[1,1,0]
	v_fma_mix_f32 v10, v20, v76, v16 op_sel:[0,0,0] op_sel_hi:[0,1,0]
	v_fma_mix_f32 v11, v20, v76, v17 op_sel:[0,1,0] op_sel_hi:[0,1,0]
	v_fma_mix_f32 v12, v20, v77, v18 op_sel:[0,0,0] op_sel_hi:[0,1,0]
	v_fma_mix_f32 v13, v20, v77, v19 op_sel:[0,1,0] op_sel_hi:[0,1,0]
	s_waitcnt lgkmcnt(4)
	ds_read_b64 v[36:37], v6 offset:2072
	ds_read_b128 v[38:41], v6 offset:2320
	ds_read_b128 v[42:45], v6 offset:2576
	ds_read_u16 v46, v7 offset:2064
	v_fma_mix_f32 v14, v10, v86, 0 op_sel:[0,0,0] op_sel_hi:[0,1,0]
	v_fma_mix_f32 v15, v12, v87, 0 op_sel:[0,0,0] op_sel_hi:[0,1,0]
	v_fma_mix_f32 v14, v11, v86, v14 op_sel:[0,1,0] op_sel_hi:[0,1,0]
	v_fma_mix_f32 v15, v13, v87, v15 op_sel:[0,1,0] op_sel_hi:[0,1,0]
	v_fma_mix_f32 v58, v10, v80, 0 op_sel:[0,0,0] op_sel_hi:[0,1,0]
	v_fma_mix_f32 v16, v10, v84, 0 op_sel:[0,0,0] op_sel_hi:[0,1,0]
	v_add_f32_e32 v20, v14, v15
	v_fma_mix_f32 v58, v11, v80, v58 op_sel:[0,1,0] op_sel_hi:[0,1,0]
	v_fma_mix_f32 v17, v11, v84, 0 op_sel:[0,1,0] op_sel_hi:[0,1,0]
	v_add_f32_dpp v20, v20, v20 quad_perm:[1,0,3,2] row_mask:0xf bank_mask:0xf bound_ctrl:1
	v_fma_mix_f32 v58, v12, v81, v58 op_sel:[0,0,0] op_sel_hi:[0,1,0]
	v_fma_mix_f32 v18, v12, v85, 0 op_sel:[0,0,0] op_sel_hi:[0,1,0]
	v_add_f32_dpp v20, v20, v20 quad_perm:[2,3,0,1] row_mask:0xf bank_mask:0xf bound_ctrl:1
	v_fma_mix_f32 v58, v13, v81, v58 op_sel:[0,1,0] op_sel_hi:[0,1,0]
	v_fma_mix_f32 v19, v13, v85, 0 op_sel:[0,1,0] op_sel_hi:[0,1,0]
	v_add_f32_dpp v20, v20, v20 row_half_mirror row_mask:0xf bank_mask:0xf bound_ctrl:1
	v_fma_mix_f32 v16, v94, v90, v16 op_sel:[0,0,0] op_sel_hi:[1,1,0]
	v_fma_mix_f32 v17, v94, v90, v17 op_sel:[0,1,0] op_sel_hi:[1,1,0]
	v_add_f32_dpp v20, v20, v20 row_mirror row_mask:0xf bank_mask:0xf bound_ctrl:1
	v_fma_mix_f32 v18, v94, v91, v18 op_sel:[0,0,0] op_sel_hi:[1,1,0]
	v_fma_mix_f32 v19, v94, v91, v19 op_sel:[0,1,0] op_sel_hi:[1,1,0]
	v_fma_mix_f32 v10, v20, v88, v16 op_sel:[0,0,0] op_sel_hi:[0,1,0]
	v_fma_mix_f32 v11, v20, v88, v17 op_sel:[0,1,0] op_sel_hi:[0,1,0]
	v_fma_mix_f32 v12, v20, v89, v18 op_sel:[0,0,0] op_sel_hi:[0,1,0]
	v_fma_mix_f32 v13, v20, v89, v19 op_sel:[0,1,0] op_sel_hi:[0,1,0]
	s_waitcnt lgkmcnt(4)
	ds_read_b64 v[72:73], v6 offset:1048
	ds_read_b128 v[74:77], v6 offset:1296
	ds_read_b128 v[78:81], v6 offset:1552
	ds_read_u16 v82, v7 offset:1040
	v_fma_mix_f32 v14, v10, v26, 0 op_sel:[0,0,0] op_sel_hi:[0,1,0]
	v_fma_mix_f32 v15, v12, v27, 0 op_sel:[0,0,0] op_sel_hi:[0,1,0]
	v_fma_mix_f32 v14, v11, v26, v14 op_sel:[0,1,0] op_sel_hi:[0,1,0]
	v_fma_mix_f32 v15, v13, v27, v15 op_sel:[0,1,0] op_sel_hi:[0,1,0]
	v_fma_mix_f32 v59, v10, v92, 0 op_sel:[0,0,0] op_sel_hi:[0,1,0]
	v_fma_mix_f32 v16, v10, v24, 0 op_sel:[0,0,0] op_sel_hi:[0,1,0]
	v_add_f32_e32 v20, v14, v15
	v_fma_mix_f32 v59, v11, v92, v59 op_sel:[0,1,0] op_sel_hi:[0,1,0]
	v_fma_mix_f32 v17, v11, v24, 0 op_sel:[0,1,0] op_sel_hi:[0,1,0]
	v_add_f32_dpp v20, v20, v20 quad_perm:[1,0,3,2] row_mask:0xf bank_mask:0xf bound_ctrl:1
	v_fma_mix_f32 v59, v12, v93, v59 op_sel:[0,0,0] op_sel_hi:[0,1,0]
	v_fma_mix_f32 v18, v12, v25, 0 op_sel:[0,0,0] op_sel_hi:[0,1,0]
	v_add_f32_dpp v20, v20, v20 quad_perm:[2,3,0,1] row_mask:0xf bank_mask:0xf bound_ctrl:1
	v_fma_mix_f32 v59, v13, v93, v59 op_sel:[0,1,0] op_sel_hi:[0,1,0]
	v_fma_mix_f32 v19, v13, v25, 0 op_sel:[0,1,0] op_sel_hi:[0,1,0]
	v_add_f32_dpp v20, v20, v20 row_half_mirror row_mask:0xf bank_mask:0xf bound_ctrl:1
	v_fma_mix_f32 v16, v34, v30, v16 op_sel:[0,0,0] op_sel_hi:[1,1,0]
	v_fma_mix_f32 v17, v34, v30, v17 op_sel:[0,1,0] op_sel_hi:[1,1,0]
	v_add_f32_dpp v20, v20, v20 row_mirror row_mask:0xf bank_mask:0xf bound_ctrl:1
	v_fma_mix_f32 v18, v34, v31, v18 op_sel:[0,0,0] op_sel_hi:[1,1,0]
	v_fma_mix_f32 v19, v34, v31, v19 op_sel:[0,1,0] op_sel_hi:[1,1,0]
	v_fma_mix_f32 v10, v20, v28, v16 op_sel:[0,0,0] op_sel_hi:[0,1,0]
	v_fma_mix_f32 v11, v20, v28, v17 op_sel:[0,1,0] op_sel_hi:[0,1,0]
	v_fma_mix_f32 v12, v20, v29, v18 op_sel:[0,0,0] op_sel_hi:[0,1,0]
	v_fma_mix_f32 v13, v20, v29, v19 op_sel:[0,1,0] op_sel_hi:[0,1,0]
	s_waitcnt lgkmcnt(4)
; DEVINL u16 f2bf(float a) { return (u16)(pk2(a, 0.f) & 0xffffu); }
; #define RW_STEP2(B) RW_STEP(B, WvA, XA, KrA, vhA, WvB, XB, KrB, vhB); RW_STEP((B) + 1, WvB, XB, KrB, vhB, WvA, XA, KrA, vhA)
; #define RW_STEP4(B) RW_STEP2(B); RW_STEP2((B) + 2)
; template <int DIR>
; DEVINL void rwkv_scan_dir(const Params& p, int task, int lane, int wave) {
;     ...
;   for (int st = 0; st < 4096; st += 32) {
;     RW_STEP(0, WvA, XA, KrA, vhA, WvB, XB, KrB, vhB);
;     if (st > 0) { const int q0 = st - 16 + seg; yo[(long)(DIR ? (4095 - q0) : q0) * 1024] = f2bf(ykeep); }
;     RW_STEP(1, WvB, XB, KrB, vhB, WvA, XA, KrA, vhA);
;     RW_STEP2(2); RW_STEP4(4); RW_STEP4(8); RW_STEP4(12);
;     RW_STEP(16, WvA, XA, KrA, vhA, WvB, XB, KrB, vhB);
;     { const int q0 = st + seg; yo[(long)(DIR ? (4095 - q0) : q0) * 1024] = f2bf(ykeep); }
;     RW_STEP(17, WvB, XB, KrB, vhB, WvA, XA, KrA, vhA);
;     RW_STEP2(18); RW_STEP4(20); RW_STEP4(24); RW_STEP4(28);
;   }
	ds_read_b128 v[100:103], v9
	ds_read_b128 v[104:107], v9 offset:16
	ds_read_b64 v[84:85], v6 offset:24
	ds_read_b128 v[86:89], v6 offset:272
	ds_read_b128 v[90:93], v6 offset:528
	ds_read_u16 v94, v7 offset:16
	v_fma_mix_f32 v14, v10, v38, 0 op_sel:[0,0,0] op_sel_hi:[0,1,0]
	v_fma_mix_f32 v15, v12, v39, 0 op_sel:[0,0,0] op_sel_hi:[0,1,0]
	v_fma_mix_f32 v14, v11, v38, v14 op_sel:[0,1,0] op_sel_hi:[0,1,0]
	v_fma_mix_f32 v15, v13, v39, v15 op_sel:[0,1,0] op_sel_hi:[0,1,0]
	v_fma_mix_f32 v60, v10, v32, 0 op_sel:[0,0,0] op_sel_hi:[0,1,0]
	v_fma_mix_f32 v16, v10, v36, 0 op_sel:[0,0,0] op_sel_hi:[0,1,0]
	v_add_f32_e32 v20, v14, v15
	v_fma_mix_f32 v60, v11, v32, v60 op_sel:[0,1,0] op_sel_hi:[0,1,0]
	v_fma_mix_f32 v17, v11, v36, 0 op_sel:[0,1,0] op_sel_hi:[0,1,0]
	v_add_f32_dpp v20, v20, v20 quad_perm:[1,0,3,2] row_mask:0xf bank_mask:0xf bound_ctrl:1
	v_fma_mix_f32 v60, v12, v33, v60 op_sel:[0,0,0] op_sel_hi:[0,1,0]
	v_fma_mix_f32 v18, v12, v37, 0 op_sel:[0,0,0] op_sel_hi:[0,1,0]
	v_add_f32_dpp v20, v20, v20 quad_perm:[2,3,0,1] row_mask:0xf bank_mask:0xf bound_ctrl:1
	v_fma_mix_f32 v60, v13, v33, v60 op_sel:[0,1,0] op_sel_hi:[0,1,0]
	v_fma_mix_f32 v19, v13, v37, 0 op_sel:[0,1,0] op_sel_hi:[0,1,0]
	v_add_f32_dpp v20, v20, v20 row_half_mirror row_mask:0xf bank_mask:0xf bound_ctrl:1
	v_fma_mix_f32 v16, v46, v42, v16 op_sel:[0,0,0] op_sel_hi:[1,1,0]
	v_fma_mix_f32 v17, v46, v42, v17 op_sel:[0,1,0] op_sel_hi:[1,1,0]
	v_add_f32_dpp v20, v20, v20 row_mirror row_mask:0xf bank_mask:0xf bound_ctrl:1
	v_fma_mix_f32 v18, v46, v43, v18 op_sel:[0,0,0] op_sel_hi:[1,1,0]
	v_fma_mix_f32 v19, v46, v43, v19 op_sel:[0,1,0] op_sel_hi:[1,1,0]
	v_fma_mix_f32 v10, v20, v40, v16 op_sel:[0,0,0] op_sel_hi:[0,1,0]
	v_fma_mix_f32 v11, v20, v40, v17 op_sel:[0,1,0] op_sel_hi:[0,1,0]
	v_fma_mix_f32 v12, v20, v41, v18 op_sel:[0,0,0] op_sel_hi:[0,1,0]
	v_fma_mix_f32 v13, v20, v41, v19 op_sel:[0,1,0] op_sel_hi:[0,1,0]
	s_waitcnt lgkmcnt(4)
	v_add_u32_e32 v6, 0xffffc000, v6
	v_add_u32_e32 v7, 0xffffc000, v7
	v_and_b32_e32 v6, 0x1ffff, v6
	v_and_b32_e32 v7, 0x1ffff, v7
	ds_read_b64 v[24:25], v6 offset:15384
	ds_read_b128 v[26:29], v6 offset:15632
	ds_read_b128 v[30:33], v6 offset:15888
	ds_read_u16 v34, v7 offset:15376
	v_fma_mix_f32 v14, v10, v74, 0 op_sel:[0,0,0] op_sel_hi:[0,1,0]
	v_fma_mix_f32 v15, v12, v75, 0 op_sel:[0,0,0] op_sel_hi:[0,1,0]
	v_fma_mix_f32 v14, v11, v74, v14 op_sel:[0,1,0] op_sel_hi:[0,1,0]
	v_fma_mix_f32 v15, v13, v75, v15 op_sel:[0,1,0] op_sel_hi:[0,1,0]
	v_fma_mix_f32 v61, v10, v44, 0 op_sel:[0,0,0] op_sel_hi:[0,1,0]
	v_fma_mix_f32 v16, v10, v72, 0 op_sel:[0,0,0] op_sel_hi:[0,1,0]
	v_add_f32_e32 v20, v14, v15
	v_fma_mix_f32 v61, v11, v44, v61 op_sel:[0,1,0] op_sel_hi:[0,1,0]
	v_fma_mix_f32 v17, v11, v72, 0 op_sel:[0,1,0] op_sel_hi:[0,1,0]
	v_add_f32_dpp v20, v20, v20 quad_perm:[1,0,3,2] row_mask:0xf bank_mask:0xf bound_ctrl:1
	v_fma_mix_f32 v61, v12, v45, v61 op_sel:[0,0,0] op_sel_hi:[0,1,0]
	v_fma_mix_f32 v18, v12, v73, 0 op_sel:[0,0,0] op_sel_hi:[0,1,0]
	v_add_f32_dpp v20, v20, v20 quad_perm:[2,3,0,1] row_mask:0xf bank_mask:0xf bound_ctrl:1
	v_fma_mix_f32 v61, v13, v45, v61 op_sel:[0,1,0] op_sel_hi:[0,1,0]
	v_fma_mix_f32 v19, v13, v73, 0 op_sel:[0,1,0] op_sel_hi:[0,1,0]
	v_add_f32_dpp v20, v20, v20 row_half_mirror row_mask:0xf bank_mask:0xf bound_ctrl:1
	v_fma_mix_f32 v16, v82, v78, v16 op_sel:[0,0,0] op_sel_hi:[1,1,0]
	v_fma_mix_f32 v17, v82, v78, v17 op_sel:[0,1,0] op_sel_hi:[1,1,0]
	v_add_f32_dpp v20, v20, v20 row_mirror row_mask:0xf bank_mask:0xf bound_ctrl:1
	v_fma_mix_f32 v18, v82, v79, v18 op_sel:[0,0,0] op_sel_hi:[1,1,0]
	v_fma_mix_f32 v19, v82, v79, v19 op_sel:[0,1,0] op_sel_hi:[1,1,0]
	v_fma_mix_f32 v10, v20, v76, v16 op_sel:[0,0,0] op_sel_hi:[0,1,0]
	v_fma_mix_f32 v11, v20, v76, v17 op_sel:[0,1,0] op_sel_hi:[0,1,0]
	v_fma_mix_f32 v12, v20, v77, v18 op_sel:[0,0,0] op_sel_hi:[0,1,0]
	v_fma_mix_f32 v13, v20, v77, v19 op_sel:[0,1,0] op_sel_hi:[0,1,0]
	s_waitcnt lgkmcnt(4)
	ds_read_b64 v[36:37], v6 offset:14360
	ds_read_b128 v[38:41], v6 offset:14608
	ds_read_b128 v[42:45], v6 offset:14864
	ds_read_u16 v46, v7 offset:14352
	v_fma_mix_f32 v14, v10, v86, 0 op_sel:[0,0,0] op_sel_hi:[0,1,0]
	v_fma_mix_f32 v15, v12, v87, 0 op_sel:[0,0,0] op_sel_hi:[0,1,0]
	v_fma_mix_f32 v14, v11, v86, v14 op_sel:[0,1,0] op_sel_hi:[0,1,0]
	v_fma_mix_f32 v15, v13, v87, v15 op_sel:[0,1,0] op_sel_hi:[0,1,0]
	v_fma_mix_f32 v62, v10, v80, 0 op_sel:[0,0,0] op_sel_hi:[0,1,0]
	v_fma_mix_f32 v16, v10, v84, 0 op_sel:[0,0,0] op_sel_hi:[0,1,0]
	v_add_f32_e32 v20, v14, v15
	v_fma_mix_f32 v62, v11, v80, v62 op_sel:[0,1,0] op_sel_hi:[0,1,0]
	v_fma_mix_f32 v17, v11, v84, 0 op_sel:[0,1,0] op_sel_hi:[0,1,0]
	v_add_f32_dpp v20, v20, v20 quad_perm:[1,0,3,2] row_mask:0xf bank_mask:0xf bound_ctrl:1
	v_fma_mix_f32 v62, v12, v81, v62 op_sel:[0,0,0] op_sel_hi:[0,1,0]
	v_fma_mix_f32 v18, v12, v85, 0 op_sel:[0,0,0] op_sel_hi:[0,1,0]
	v_add_f32_dpp v20, v20, v20 quad_perm:[2,3,0,1] row_mask:0xf bank_mask:0xf bound_ctrl:1
	v_fma_mix_f32 v62, v13, v81, v62 op_sel:[0,1,0] op_sel_hi:[0,1,0]
	v_fma_mix_f32 v19, v13, v85, 0 op_sel:[0,1,0] op_sel_hi:[0,1,0]
	v_add_f32_dpp v20, v20, v20 row_half_mirror row_mask:0xf bank_mask:0xf bound_ctrl:1
	v_fma_mix_f32 v16, v94, v90, v16 op_sel:[0,0,0] op_sel_hi:[1,1,0]
	v_fma_mix_f32 v17, v94, v90, v17 op_sel:[0,1,0] op_sel_hi:[1,1,0]
	v_add_f32_dpp v20, v20, v20 row_mirror row_mask:0xf bank_mask:0xf bound_ctrl:1
	v_fma_mix_f32 v18, v94, v91, v18 op_sel:[0,0,0] op_sel_hi:[1,1,0]
	v_fma_mix_f32 v19, v94, v91, v19 op_sel:[0,1,0] op_sel_hi:[1,1,0]
	v_fma_mix_f32 v10, v20, v88, v16 op_sel:[0,0,0] op_sel_hi:[0,1,0]
	v_fma_mix_f32 v11, v20, v88, v17 op_sel:[0,1,0] op_sel_hi:[0,1,0]
	v_fma_mix_f32 v12, v20, v89, v18 op_sel:[0,0,0] op_sel_hi:[0,1,0]
	v_fma_mix_f32 v13, v20, v89, v19 op_sel:[0,1,0] op_sel_hi:[0,1,0]
	s_waitcnt lgkmcnt(4)
	s_add_u32 s15, s15, 1
	s_add_u32 s14, s14, 1
	v_mov_b32_e32 v69, s15
	ds_write_b32 v68, v69
	s_cmp_lt_u32 s14, 0x100
	s_cbranch_scc1 .Lrw_blk_d1
; DEVINL u16 f2bf(float a) { return (u16)(pk2(a, 0.f) & 0xffffu); }
; template <int DIR>
; DEVINL void rwkv_scan_dir(const Params& p, int task, int lane, int wave) {
;     ...
;   {
;     const float ylast = allred16(ypart);
;     ykeep = (seg == 15) ? ylast : ykeep;
;     const int q0 = 4096 - 16 + seg; yo[(long)(DIR ? (4095 - q0) : q0) * 1024] = f2bf(ykeep);
;   }
;   asm volatile("s_waitcnt vmcnt(0)" ::: "memory");
	v_fma_mix_f32 v21, v10, v92, 0 op_sel:[0,0,0] op_sel_hi:[0,1,0]
	v_fma_mix_f32 v22, v12, v93, 0 op_sel:[0,0,0] op_sel_hi:[0,1,0]
	v_fma_mix_f32 v21, v11, v92, v21 op_sel:[0,1,0] op_sel_hi:[0,1,0]
	v_fma_mix_f32 v22, v13, v93, v22 op_sel:[0,1,0] op_sel_hi:[0,1,0]
	v_add_f32_e32 v63, v21, v22
	s_nop 1
	v_add_f32_dpp v48, v48, v48 row_ror:8 row_mask:0xf bank_mask:0x3
	v_add_f32_dpp v49, v49, v49 row_ror:8 row_mask:0xf bank_mask:0x3
	v_add_f32_dpp v50, v50, v50 row_ror:8 row_mask:0xf bank_mask:0x3
	v_add_f32_dpp v51, v51, v51 row_ror:8 row_mask:0xf bank_mask:0x3
	v_add_f32_dpp v52, v52, v52 row_ror:8 row_mask:0xf bank_mask:0x3
	v_add_f32_dpp v53, v53, v53 row_ror:8 row_mask:0xf bank_mask:0x3
	v_add_f32_dpp v54, v54, v54 row_ror:8 row_mask:0xf bank_mask:0x3
	v_add_f32_dpp v55, v55, v55 row_ror:8 row_mask:0xf bank_mask:0x3
	v_add_f32_dpp v48, v56, v56 row_ror:8 row_mask:0xf bank_mask:0xc
	v_add_f32_dpp v49, v57, v57 row_ror:8 row_mask:0xf bank_mask:0xc
	v_add_f32_dpp v50, v58, v58 row_ror:8 row_mask:0xf bank_mask:0xc
	v_add_f32_dpp v51, v59, v59 row_ror:8 row_mask:0xf bank_mask:0xc
	v_add_f32_dpp v52, v60, v60 row_ror:8 row_mask:0xf bank_mask:0xc
	v_add_f32_dpp v53, v61, v61 row_ror:8 row_mask:0xf bank_mask:0xc
	v_add_f32_dpp v54, v62, v62 row_ror:8 row_mask:0xf bank_mask:0xc
	v_add_f32_dpp v55, v63, v63 row_ror:8 row_mask:0xf bank_mask:0xc
	v_add_f32_dpp v48, v48, v48 row_ror:12 row_mask:0xf bank_mask:0x5
	v_add_f32_dpp v49, v49, v49 row_ror:12 row_mask:0xf bank_mask:0x5
	v_add_f32_dpp v50, v50, v50 row_ror:12 row_mask:0xf bank_mask:0x5
	v_add_f32_dpp v51, v51, v51 row_ror:12 row_mask:0xf bank_mask:0x5
	v_add_f32_dpp v48, v52, v52 row_ror:4 row_mask:0xf bank_mask:0xa
	v_add_f32_dpp v49, v53, v53 row_ror:4 row_mask:0xf bank_mask:0xa
	v_add_f32_dpp v50, v54, v54 row_ror:4 row_mask:0xf bank_mask:0xa
	v_add_f32_dpp v51, v55, v55 row_ror:4 row_mask:0xf bank_mask:0xa
	v_add_f32_dpp v64, v48, v48 quad_perm:[2,3,0,1] row_mask:0xf bank_mask:0xf bound_ctrl:1
	v_add_f32_dpp v65, v50, v50 quad_perm:[2,3,0,1] row_mask:0xf bank_mask:0xf bound_ctrl:1
	v_cndmask_b32_e64 v56, v64, v65, s[50:51]
	v_add_f32_dpp v64, v49, v49 quad_perm:[2,3,0,1] row_mask:0xf bank_mask:0xf bound_ctrl:1
	v_add_f32_dpp v65, v51, v51 quad_perm:[2,3,0,1] row_mask:0xf bank_mask:0xf bound_ctrl:1
	v_cndmask_b32_e64 v57, v64, v65, s[50:51]
	v_add_f32_dpp v64, v56, v56 quad_perm:[1,0,3,2] row_mask:0xf bank_mask:0xf bound_ctrl:1
	s_nop 0
	v_add_f32_dpp v65, v57, v57 quad_perm:[1,0,3,2] row_mask:0xf bank_mask:0xf bound_ctrl:1
	v_cndmask_b32_e64 v66, v64, v65, s[48:49]
	v_cvt_pk_bf16_f32 v66, v66, v66
	global_store_short v8, v66, s[12:13]
	s_sub_u32 s12, s12, 0x8000
	s_subb_u32 s13, s13, 0
